# ph8 and ph13 GEMM tails also run as 128 half tiles (EpiResid rounds 3/4 and ai=1 partial-sum stores skipped in half mode)
# speedup vs baseline: 1.0315x; 1.0078x over previous
.LBB0_684:
	v_readlane_b32 s30, v255, 31
	v_readlane_b32 s31, v255, 32
	s_mov_b32 s61, s31
	s_mul_i32 s60, s8, 0xd800
	s_lshl_b64 s[30:31], s[60:61], 2
	s_add_u32 s1, s46, s30
	s_addc_u32 s40, s47, s31
	s_add_u32 s71, s46, 0x5e00000
	s_addc_u32 s78, s47, 0
	s_add_u32 s79, s1, 0x2000
	s_mov_b32 s31, s61
	s_addc_u32 s80, s40, 0
	s_lshl_b32 s60, s8, 10
	v_writelane_b32 v255, s30, 31
	v_mov_b32_e32 v195, v1
	s_waitcnt vmcnt(2)
	s_barrier
	v_writelane_b32 v255, s31, 32
	s_lshl_b64 s[30:31], s[60:61], 2
	s_waitcnt lgkmcnt(0)
	s_add_u32 s30, s18, s30
	s_addc_u32 s31, s19, s31
	s_add_u32 s81, s1, 0x4000
	s_addc_u32 s40, s40, 0
	s_ashr_i32 s1, s56, 31
	s_lshr_b32 s1, s1, 26
	s_add_i32 s1, s56, s1
	s_lshl_b32 s18, s34, 12
	s_ashr_i32 s41, s1, 6
	s_lshl_b32 s1, s35, 13
	s_and_b32 s57, s18, 0x3000
	s_add_u32 s34, s46, 0x6000000
	s_addc_u32 s35, s47, 0
	s_add_u32 s18, s2, 0x80
	s_addc_u32 s19, s3, 0
	s_add_i32 m0, s67, 0x18000
	v_lshl_add_u64 v[2:3], s[18:19], 0, v[194:195]
	v_mov_b32_e32 v171, v1
	global_load_lds_dwordx4 v[2:3], off
	s_add_i32 m0, s67, 0x1a000
	v_lshl_add_u64 v[2:3], s[18:19], 0, v[170:171]
	s_add_u32 s18, s26, 0x80
	v_mov_b32_e32 v197, v1
	s_addc_u32 s19, s27, 0
	s_add_i32 s82, s67, 0x8000
	v_mov_b32_e32 v173, v1
	global_load_lds_dwordx4 v[2:3], off
	s_mov_b32 m0, s82
	v_lshl_add_u64 v[2:3], s[18:19], 0, v[196:197]
	s_add_i32 s83, s67, 0xa000
	global_load_lds_dwordx4 v[2:3], off
	v_lshl_add_u64 v[2:3], s[18:19], 0, v[172:173]
	s_add_u32 s18, s54, 0x80
	s_mov_b32 m0, s83
	s_addc_u32 s19, s55, 0
	global_load_lds_dwordx4 v[2:3], off
	s_add_i32 m0, s67, 0x1c000
	v_lshl_add_u64 v[2:3], s[18:19], 0, v[194:195]
	global_load_lds_dwordx4 v[2:3], off
	v_lshl_add_u64 v[2:3], s[18:19], 0, v[170:171]
	s_add_i32 m0, s67, 0x1e000
	s_cmp_gt_i32 s56, 63
	global_load_lds_dwordx4 v[2:3], off
	v_and_b32_e32 v2, 15, v0
	v_and_b32_e32 v3, 48, v0
	v_lshlrev_b32_e32 v2, 6, v2
	v_lshlrev_b32_e32 v0, 2, v0
	s_cselect_b64 s[46:47], -1, 0
	s_add_i32 s84, s41, -2
	v_or_b32_e32 v4, v2, v3
	v_and_b32_e32 v0, 32, v0
	s_waitcnt vmcnt(6)
	s_cmpk_lt_u32 s43, 0x100
	v_bitop3_b32 v2, v2, v0, v3 bitop3:0x36
	v_bitop3_b32 v0, v4, s1, v0 bitop3:0xde
	s_cselect_b64 s[54:55], -1, 0
	s_add_u32 s85, s36, 0xff000000
	s_sext_i32_i8 s88, s42
	v_or_b32_e32 v222, s57, v2
	s_addc_u32 s86, s37, -1
	s_mov_b32 s87, 0
	s_mov_b32 s100, 0
	s_mov_b32 s101, 0
	v_add_u32_e32 v223, 0, v0
	s_barrier
	s_branch .LBB0_687

.LBB0_686:
	s_mov_b32 s100, s101
	s_andn2_b64 vcc, exec, s[0:1]
	s_mov_b32 s88, s36
	s_mov_b32 s0, s56
	s_mov_b64 s[2:3], s[62:63]
	s_mov_b64 s[26:27], s[60:61]
	s_cbranch_vccz .LBB0_700
.LBB0_687:
	s_add_i32 s87, s87, 1
	s_mul_i32 s1, s87, s15
	s_mul_hi_u32 s18, s87, s64
	s_add_i32 s1, s18, s1
	s_mul_i32 s18, s87, s64
	s_add_u32 s18, s18, s16
	s_addc_u32 s19, s1, s39
	s_mov_b32 s101, 0
	s_cmp_lg_u32 s87, 1
	s_cbranch_scc1 .Lh13_a
	s_movk_i32 s18, 0x140
	s_mov_b32 s19, 0
	s_cmp_gt_i32 s16, 0x7f
	s_cbranch_scc1 .Lh13_a
	s_and_b32 s101, s16, 1
	s_add_i32 s101, s101, 1
	s_lshr_b32 s18, s16, 1
	s_addk_i32 s18, 0x100
.Lh13_a:
	v_cmp_gt_i64_e32 vcc, s[18:19], v[176:177]
	v_cmp_lt_i64_e64 s[42:43], s[18:19], v[174:175]
	s_cbranch_vccnz .LBB0_689
	s_ashr_i32 s1, s18, 31
	s_lshr_b32 s1, s1, 29
	s_add_i32 s1, s18, s1
	s_ashr_i32 s19, s1, 3
	s_and_b32 s1, s1, -8
	s_sub_i32 s1, s18, s1
	s_cmp_lt_i32 s1, 0
	s_cselect_b32 s18, 41, 40
	s_mul_i32 s1, s18, s1
	s_add_i32 s1, s1, s19
	s_ashr_i32 s18, s1, 31
	s_lshr_b32 s18, s18, 28
	s_add_i32 s18, s1, s18
	s_ashr_i32 s19, s18, 4
	s_lshl_b32 s19, s19, 2
	s_sub_i32 s36, 0x50, s19
	s_min_i32 s37, s36, 4
	s_abs_i32 s36, s37
	v_cvt_f32_u32_e32 v0, s36
	s_sub_i32 s57, 0, s36
	s_and_b32 s18, s18, -16
	s_sub_i32 s1, s1, s18
	v_rcp_iflag_f32_e32 v0, v0
	s_abs_i32 s18, s1
	s_xor_b32 s56, s1, s37
	s_ashr_i32 s56, s56, 31
	v_mul_f32_e32 v0, 0x4f7ffffe, v0
	v_cvt_u32_f32_e32 v0, v0
	s_nop 0
	v_readfirstlane_b32 s60, v0
	s_mul_i32 s57, s57, s60
	s_mul_hi_u32 s57, s60, s57
	s_add_i32 s60, s60, s57
	s_mul_hi_u32 s57, s18, s60
	s_mul_i32 s60, s57, s36
	s_sub_i32 s18, s18, s60
	s_add_i32 s61, s57, 1
	s_sub_i32 s60, s18, s36
	s_cmp_ge_u32 s18, s36
	s_cselect_b32 s57, s61, s57
	s_cselect_b32 s18, s60, s18
	s_add_i32 s60, s57, 1
	s_cmp_ge_u32 s18, s36
	s_cselect_b32 s18, s60, s57
	s_xor_b32 s18, s18, s56
	s_sub_i32 s36, s18, s56
	s_mul_i32 s18, s36, s37
	s_sub_i32 s1, s1, s18
	s_add_i32 s56, s1, s19
.LBB0_689:
	s_ashr_i32 s57, s56, 31
	s_lshl_b64 s[18:19], s[56:57], 19
	s_add_u32 s60, s17, s18
	s_addc_u32 s61, s21, s19
	s_cmp_lg_u32 s101, 2
	s_cbranch_scc1 .Lh13_b
	s_add_u32 s60, s60, 0x40000
	s_addc_u32 s61, s61, 0
.Lh13_b:
	s_ashr_i32 s37, s36, 31
	s_lshl_b64 s[18:19], s[36:37], 19
	s_add_u32 s62, s22, s18
	v_mov_b32_e32 v141, 0
	s_addc_u32 s63, s23, s19
	s_andn2_b64 vcc, exec, s[46:47]
	s_waitcnt lgkmcnt(0)
	s_cbranch_vccnz .LBB0_693
	s_and_b64 s[18:19], s[42:43], exec
	s_cselect_b32 s1, s61, s27
	s_cselect_b32 s37, s60, s26
	s_cselect_b32 s57, s63, s3
	s_cselect_b32 s89, s62, s2
	s_add_u32 vcc_lo, s26, 0x100
	s_addc_u32 vcc_hi, s27, 0
	s_add_u32 s90, s2, 0x100
	s_addc_u32 s91, s3, 0
	s_add_u32 s2, s26, 0x40080
	v_mov_b32_e32 v2, 0
	s_addc_u32 s3, s27, 0
	s_mov_b32 s18, 0
	v_mov_b32_e32 v3, v2
	v_mov_b32_e32 v4, v2
	v_mov_b32_e32 v5, v2
	v_mov_b32_e32 v6, v2
	v_mov_b32_e32 v7, v2
	v_mov_b32_e32 v8, v2
	v_mov_b32_e32 v9, v2
	v_mov_b32_e32 v18, v2
	v_mov_b32_e32 v19, v2
	v_mov_b32_e32 v20, v2
	v_mov_b32_e32 v21, v2
	v_mov_b32_e32 v22, v2
	v_mov_b32_e32 v23, v2
	v_mov_b32_e32 v24, v2
	v_mov_b32_e32 v25, v2
	v_mov_b32_e32 v34, v2
	v_mov_b32_e32 v35, v2
	v_mov_b32_e32 v36, v2
	v_mov_b32_e32 v37, v2
	v_mov_b32_e32 v38, v2
	v_mov_b32_e32 v39, v2
	v_mov_b32_e32 v40, v2
	v_mov_b32_e32 v41, v2
	v_mov_b32_e32 v50, v2
	v_mov_b32_e32 v51, v2
	v_mov_b32_e32 v52, v2
	v_mov_b32_e32 v53, v2
	v_mov_b32_e32 v54, v2
	v_mov_b32_e32 v55, v2
	v_mov_b32_e32 v56, v2
	v_mov_b32_e32 v57, v2
	v_mov_b32_e32 v10, v2
	v_mov_b32_e32 v11, v2
	v_mov_b32_e32 v12, v2
	v_mov_b32_e32 v13, v2
	v_mov_b32_e32 v14, v2
	v_mov_b32_e32 v15, v2
	v_mov_b32_e32 v16, v2
	v_mov_b32_e32 v17, v2
	v_mov_b32_e32 v26, v2
	v_mov_b32_e32 v27, v2
	v_mov_b32_e32 v28, v2
	v_mov_b32_e32 v29, v2
	v_mov_b32_e32 v30, v2
	v_mov_b32_e32 v31, v2
	v_mov_b32_e32 v32, v2
	v_mov_b32_e32 v33, v2
	v_mov_b32_e32 v42, v2
	v_mov_b32_e32 v43, v2
	v_mov_b32_e32 v44, v2
	v_mov_b32_e32 v45, v2
	v_mov_b32_e32 v46, v2
	v_mov_b32_e32 v47, v2
	v_mov_b32_e32 v48, v2
	v_mov_b32_e32 v49, v2
	v_mov_b32_e32 v58, v2
	v_mov_b32_e32 v59, v2
	v_mov_b32_e32 v60, v2
	v_mov_b32_e32 v61, v2
	v_mov_b32_e32 v62, v2
	v_mov_b32_e32 v63, v2
	v_mov_b32_e32 v64, v2
	v_mov_b32_e32 v65, v2
	v_mov_b32_e32 v82, v2
	v_mov_b32_e32 v83, v2
	v_mov_b32_e32 v84, v2
	v_mov_b32_e32 v85, v2
	v_mov_b32_e32 v86, v2
	v_mov_b32_e32 v87, v2
	v_mov_b32_e32 v88, v2
	v_mov_b32_e32 v89, v2
	v_mov_b32_e32 v98, v2
	v_mov_b32_e32 v99, v2
	v_mov_b32_e32 v100, v2
	v_mov_b32_e32 v101, v2
	v_mov_b32_e32 v102, v2
	v_mov_b32_e32 v103, v2
	v_mov_b32_e32 v104, v2
	v_mov_b32_e32 v105, v2
	v_mov_b32_e32 v114, v2
	v_mov_b32_e32 v115, v2
	v_mov_b32_e32 v116, v2
	v_mov_b32_e32 v117, v2
	v_mov_b32_e32 v118, v2
	v_mov_b32_e32 v119, v2
	v_mov_b32_e32 v120, v2
	v_mov_b32_e32 v121, v2
	v_mov_b32_e32 v130, v2
	v_mov_b32_e32 v131, v2
	v_mov_b32_e32 v132, v2
	v_mov_b32_e32 v133, v2
	v_mov_b32_e32 v134, v2
	v_mov_b32_e32 v135, v2
	v_mov_b32_e32 v136, v2
	v_mov_b32_e32 v137, v2
	v_mov_b32_e32 v90, v2
	v_mov_b32_e32 v91, v2
	v_mov_b32_e32 v92, v2
	v_mov_b32_e32 v93, v2
	v_mov_b32_e32 v94, v2
	v_mov_b32_e32 v95, v2
	v_mov_b32_e32 v96, v2
	v_mov_b32_e32 v97, v2
	v_mov_b32_e32 v106, v2
	v_mov_b32_e32 v107, v2
	v_mov_b32_e32 v108, v2
	v_mov_b32_e32 v109, v2
	v_mov_b32_e32 v110, v2
	v_mov_b32_e32 v111, v2
	v_mov_b32_e32 v112, v2
	v_mov_b32_e32 v113, v2
	v_mov_b32_e32 v122, v2
	v_mov_b32_e32 v123, v2
	v_mov_b32_e32 v124, v2
	v_mov_b32_e32 v125, v2
	v_mov_b32_e32 v126, v2
	v_mov_b32_e32 v127, v2
	v_mov_b32_e32 v128, v2
	v_mov_b32_e32 v129, v2
	v_mov_b32_e32 v142, v2
	v_mov_b32_e32 v143, v2
	v_mov_b32_e32 v144, v2
	v_mov_b32_e32 v145, v2
	v_mov_b32_e32 v138, v2
	v_mov_b32_e32 v139, v2
	v_mov_b32_e32 v140, v2
	v_mov_b32_e32 v141, v2
.LBB0_691:
	s_add_i32 s92, s18, 2
	s_cmp_eq_u32 s84, s18
	s_cselect_b32 s18, s37, vcc_lo
	s_cselect_b32 s19, s1, vcc_hi
	s_cselect_b32 s72, s89, s90
	s_cselect_b32 s73, s57, s91
	s_add_u32 s26, s18, 0x80
	s_addc_u32 s27, s19, 0
	s_add_i32 s93, 0, 0x10000
	v_add_u32_e32 v0, s93, v222
	s_add_i32 s96, 0, 0x14000
	ds_read_b128 v[66:69], v0
	ds_read_b128 v[70:73], v0 offset:1024
	ds_read_b128 v[74:77], v0 offset:2048
	ds_read_b128 v[78:81], v0 offset:3072
	v_add_u32_e32 v0, s96, v222
	ds_read_b128 v[146:149], v0
	ds_read_b128 v[150:153], v0 offset:1024
	ds_read_b128 v[154:157], v0 offset:2048
	ds_read_b128 v[158:161], v0 offset:3072
	s_mov_b64 s[94:95], s[2:3]
	ds_read_b128 v[162:165], v223
	ds_read_b128 v[166:169], v223 offset:1024
	ds_read_b128 v[198:201], v223 offset:2048
	ds_read_b128 v[202:205], v223 offset:3072
	ds_read_b128 v[206:209], v223 offset:4096
	ds_read_b128 v[210:213], v223 offset:5120
	ds_read_b128 v[214:217], v223 offset:6144
	ds_read_b128 v[218:221], v223 offset:7168
	s_add_i32 m0, s67, 0xc000
	v_lshl_add_u64 v[224:225], s[94:95], 0, v[196:197]
	global_load_lds_dwordx4 v[224:225], off
	v_lshl_add_u64 v[224:225], s[94:95], 0, v[172:173]
	s_add_i32 m0, s67, 0xe000
	s_nop 0
	global_load_lds_dwordx4 v[224:225], off
	s_waitcnt vmcnt(8)
	s_waitcnt lgkmcnt(0)
	s_barrier
	s_setprio 1
	s_waitcnt lgkmcnt(0)
	v_mfma_f32_16x16x32_bf16 v[138:141], v[66:69], v[162:165], v[138:141]
	v_mfma_f32_16x16x32_bf16 v[142:145], v[74:77], v[162:165], v[142:145]
	v_mfma_f32_16x16x32_bf16 v[126:129], v[66:69], v[198:201], v[126:129]
	v_mfma_f32_16x16x32_bf16 v[122:125], v[74:77], v[198:201], v[122:125]
	v_mfma_f32_16x16x32_bf16 v[110:113], v[66:69], v[206:209], v[110:113]
	v_mfma_f32_16x16x32_bf16 v[106:109], v[74:77], v[206:209], v[106:109]
	v_mfma_f32_16x16x32_bf16 v[94:97], v[66:69], v[214:217], v[94:97]
	v_mfma_f32_16x16x32_bf16 v[90:93], v[74:77], v[214:217], v[90:93]
	v_mfma_f32_16x16x32_bf16 v[138:141], v[70:73], v[166:169], v[138:141]
	v_mfma_f32_16x16x32_bf16 v[142:145], v[78:81], v[166:169], v[142:145]
	v_mfma_f32_16x16x32_bf16 v[126:129], v[70:73], v[202:205], v[126:129]
	v_mfma_f32_16x16x32_bf16 v[122:125], v[78:81], v[202:205], v[122:125]
	v_mfma_f32_16x16x32_bf16 v[110:113], v[70:73], v[210:213], v[110:113]
	v_mfma_f32_16x16x32_bf16 v[106:109], v[78:81], v[210:213], v[106:109]
	v_mfma_f32_16x16x32_bf16 v[94:97], v[70:73], v[218:221], v[94:97]
	v_mfma_f32_16x16x32_bf16 v[90:93], v[78:81], v[218:221], v[90:93]
	v_mfma_f32_16x16x32_bf16 v[134:137], v[146:149], v[162:165], v[134:137]
	v_mfma_f32_16x16x32_bf16 v[130:133], v[154:157], v[162:165], v[130:133]
	v_mfma_f32_16x16x32_bf16 v[118:121], v[146:149], v[198:201], v[118:121]
	v_mfma_f32_16x16x32_bf16 v[114:117], v[154:157], v[198:201], v[114:117]
	v_mfma_f32_16x16x32_bf16 v[102:105], v[146:149], v[206:209], v[102:105]
	v_mfma_f32_16x16x32_bf16 v[98:101], v[154:157], v[206:209], v[98:101]
	v_mfma_f32_16x16x32_bf16 v[86:89], v[146:149], v[214:217], v[86:89]
	v_mfma_f32_16x16x32_bf16 v[82:85], v[154:157], v[214:217], v[82:85]
	v_mfma_f32_16x16x32_bf16 v[134:137], v[150:153], v[166:169], v[134:137]
	v_mfma_f32_16x16x32_bf16 v[130:133], v[158:161], v[166:169], v[130:133]
	v_mfma_f32_16x16x32_bf16 v[118:121], v[150:153], v[202:205], v[118:121]
	v_mfma_f32_16x16x32_bf16 v[114:117], v[158:161], v[202:205], v[114:117]
	v_mfma_f32_16x16x32_bf16 v[102:105], v[150:153], v[210:213], v[102:105]
	v_mfma_f32_16x16x32_bf16 v[98:101], v[158:161], v[210:213], v[98:101]
	v_mfma_f32_16x16x32_bf16 v[86:89], v[150:153], v[218:221], v[86:89]
	v_mfma_f32_16x16x32_bf16 v[82:85], v[158:161], v[218:221], v[82:85]
	s_setprio 0
	s_barrier
	s_mov_b64 s[94:95], s[72:73]
	s_add_i32 s93, s93, s25
	ds_read_b128 v[162:165], v223 offset:16384
	ds_read_b128 v[166:169], v223 offset:17408
	ds_read_b128 v[198:201], v223 offset:18432
	ds_read_b128 v[202:205], v223 offset:19456
	ds_read_b128 v[206:209], v223 offset:20480
	ds_read_b128 v[210:213], v223 offset:21504
	ds_read_b128 v[214:217], v223 offset:22528
	ds_read_b128 v[218:221], v223 offset:23552
	s_mov_b32 m0, s93
	v_lshl_add_u64 v[224:225], s[94:95], 0, v[194:195]
	global_load_lds_dwordx4 v[224:225], off
	s_add_i32 m0, s93, 0x2000
	v_lshl_add_u64 v[224:225], s[94:95], 0, v[170:171]
	s_add_u32 s94, s72, 0x40000
	s_addc_u32 s95, s73, 0
	s_add_i32 s93, s96, s25
	global_load_lds_dwordx4 v[224:225], off
	s_mov_b32 m0, s93
	v_lshl_add_u64 v[224:225], s[94:95], 0, v[194:195]
	global_load_lds_dwordx4 v[224:225], off
	v_lshl_add_u64 v[224:225], s[94:95], 0, v[170:171]
	s_add_i32 m0, s93, 0x2000
	s_mov_b64 s[94:95], s[18:19]
	global_load_lds_dwordx4 v[224:225], off
	s_mov_b32 m0, s67
	v_lshl_add_u64 v[224:225], s[94:95], 0, v[196:197]
	global_load_lds_dwordx4 v[224:225], off
	v_lshl_add_u64 v[224:225], s[94:95], 0, v[172:173]
	s_mov_b32 m0, s68
	s_nop 0
	global_load_lds_dwordx4 v[224:225], off
	s_waitcnt vmcnt(8)
	s_waitcnt lgkmcnt(0)
	s_barrier
	s_setprio 1
	s_waitcnt lgkmcnt(0)
	s_cmp_lg_u32 s100, 0
	s_cbranch_scc1 .Lh13_m0
	v_mfma_f32_16x16x32_bf16 v[62:65], v[66:69], v[162:165], v[62:65]
	v_mfma_f32_16x16x32_bf16 v[58:61], v[74:77], v[162:165], v[58:61]
	v_mfma_f32_16x16x32_bf16 v[46:49], v[66:69], v[198:201], v[46:49]
	v_mfma_f32_16x16x32_bf16 v[42:45], v[74:77], v[198:201], v[42:45]
	v_mfma_f32_16x16x32_bf16 v[30:33], v[66:69], v[206:209], v[30:33]
	v_mfma_f32_16x16x32_bf16 v[26:29], v[74:77], v[206:209], v[26:29]
	v_mfma_f32_16x16x32_bf16 v[14:17], v[66:69], v[214:217], v[14:17]
	v_mfma_f32_16x16x32_bf16 v[10:13], v[74:77], v[214:217], v[10:13]
	v_mfma_f32_16x16x32_bf16 v[62:65], v[70:73], v[166:169], v[62:65]
	v_mfma_f32_16x16x32_bf16 v[58:61], v[78:81], v[166:169], v[58:61]
	v_mfma_f32_16x16x32_bf16 v[46:49], v[70:73], v[202:205], v[46:49]
	v_mfma_f32_16x16x32_bf16 v[42:45], v[78:81], v[202:205], v[42:45]
	v_mfma_f32_16x16x32_bf16 v[30:33], v[70:73], v[210:213], v[30:33]
	v_mfma_f32_16x16x32_bf16 v[26:29], v[78:81], v[210:213], v[26:29]
	v_mfma_f32_16x16x32_bf16 v[14:17], v[70:73], v[218:221], v[14:17]
	v_mfma_f32_16x16x32_bf16 v[10:13], v[78:81], v[218:221], v[10:13]
	v_mfma_f32_16x16x32_bf16 v[54:57], v[146:149], v[162:165], v[54:57]
	v_mfma_f32_16x16x32_bf16 v[50:53], v[154:157], v[162:165], v[50:53]
	v_mfma_f32_16x16x32_bf16 v[38:41], v[146:149], v[198:201], v[38:41]
	v_mfma_f32_16x16x32_bf16 v[34:37], v[154:157], v[198:201], v[34:37]
	v_mfma_f32_16x16x32_bf16 v[22:25], v[146:149], v[206:209], v[22:25]
	v_mfma_f32_16x16x32_bf16 v[18:21], v[154:157], v[206:209], v[18:21]
	v_mfma_f32_16x16x32_bf16 v[6:9], v[146:149], v[214:217], v[6:9]
	v_mfma_f32_16x16x32_bf16 v[2:5], v[154:157], v[214:217], v[2:5]
	v_mfma_f32_16x16x32_bf16 v[54:57], v[150:153], v[166:169], v[54:57]
	v_mfma_f32_16x16x32_bf16 v[50:53], v[158:161], v[166:169], v[50:53]
	v_mfma_f32_16x16x32_bf16 v[38:41], v[150:153], v[202:205], v[38:41]
	v_mfma_f32_16x16x32_bf16 v[34:37], v[158:161], v[202:205], v[34:37]
	v_mfma_f32_16x16x32_bf16 v[22:25], v[150:153], v[210:213], v[22:25]
	v_mfma_f32_16x16x32_bf16 v[18:21], v[158:161], v[210:213], v[18:21]
	v_mfma_f32_16x16x32_bf16 v[6:9], v[150:153], v[218:221], v[6:9]
	v_mfma_f32_16x16x32_bf16 v[2:5], v[158:161], v[218:221], v[2:5]
.Lh13_m0:
	s_setprio 0
	s_barrier
	s_add_i32 s93, 0, 0x18000
	v_add_u32_e32 v0, s93, v222
	s_add_i32 s94, 0, 0x1c000
	ds_read_b128 v[66:69], v0
	ds_read_b128 v[70:73], v0 offset:1024
	ds_read_b128 v[74:77], v0 offset:2048
	ds_read_b128 v[78:81], v0 offset:3072
	v_add_u32_e32 v0, s94, v222
	ds_read_b128 v[146:149], v0
	ds_read_b128 v[150:153], v0 offset:1024
	ds_read_b128 v[154:157], v0 offset:2048
	ds_read_b128 v[158:161], v0 offset:3072
	s_add_u32 s18, s18, 0x40000
	s_addc_u32 s19, s19, 0
	s_mov_b32 m0, s69
	ds_read_b128 v[162:165], v223 offset:32768
	ds_read_b128 v[166:169], v223 offset:33792
	ds_read_b128 v[198:201], v223 offset:34816
	ds_read_b128 v[202:205], v223 offset:35840
	ds_read_b128 v[206:209], v223 offset:36864
	ds_read_b128 v[210:213], v223 offset:37888
	ds_read_b128 v[214:217], v223 offset:38912
	ds_read_b128 v[218:221], v223 offset:39936
	s_nop 0
	v_lshl_add_u64 v[224:225], s[18:19], 0, v[196:197]
	global_load_lds_dwordx4 v[224:225], off
	v_lshl_add_u64 v[224:225], s[18:19], 0, v[172:173]
	s_mov_b32 m0, s70
	s_nop 0
	global_load_lds_dwordx4 v[224:225], off
	s_waitcnt vmcnt(8)
	s_waitcnt lgkmcnt(0)
	s_barrier
	s_setprio 1
	s_waitcnt lgkmcnt(0)
	v_mfma_f32_16x16x32_bf16 v[138:141], v[66:69], v[162:165], v[138:141]
	v_mfma_f32_16x16x32_bf16 v[142:145], v[74:77], v[162:165], v[142:145]
	v_mfma_f32_16x16x32_bf16 v[126:129], v[66:69], v[198:201], v[126:129]
	v_mfma_f32_16x16x32_bf16 v[122:125], v[74:77], v[198:201], v[122:125]
	v_mfma_f32_16x16x32_bf16 v[110:113], v[66:69], v[206:209], v[110:113]
	v_mfma_f32_16x16x32_bf16 v[106:109], v[74:77], v[206:209], v[106:109]
	v_mfma_f32_16x16x32_bf16 v[94:97], v[66:69], v[214:217], v[94:97]
	v_mfma_f32_16x16x32_bf16 v[90:93], v[74:77], v[214:217], v[90:93]
	v_mfma_f32_16x16x32_bf16 v[138:141], v[70:73], v[166:169], v[138:141]
	v_mfma_f32_16x16x32_bf16 v[142:145], v[78:81], v[166:169], v[142:145]
	v_mfma_f32_16x16x32_bf16 v[126:129], v[70:73], v[202:205], v[126:129]
	v_mfma_f32_16x16x32_bf16 v[122:125], v[78:81], v[202:205], v[122:125]
	v_mfma_f32_16x16x32_bf16 v[110:113], v[70:73], v[210:213], v[110:113]
	v_mfma_f32_16x16x32_bf16 v[106:109], v[78:81], v[210:213], v[106:109]
	v_mfma_f32_16x16x32_bf16 v[94:97], v[70:73], v[218:221], v[94:97]
	v_mfma_f32_16x16x32_bf16 v[90:93], v[78:81], v[218:221], v[90:93]
	v_mfma_f32_16x16x32_bf16 v[134:137], v[146:149], v[162:165], v[134:137]
	v_mfma_f32_16x16x32_bf16 v[130:133], v[154:157], v[162:165], v[130:133]
	v_mfma_f32_16x16x32_bf16 v[118:121], v[146:149], v[198:201], v[118:121]
	v_mfma_f32_16x16x32_bf16 v[114:117], v[154:157], v[198:201], v[114:117]
	v_mfma_f32_16x16x32_bf16 v[102:105], v[146:149], v[206:209], v[102:105]
	v_mfma_f32_16x16x32_bf16 v[98:101], v[154:157], v[206:209], v[98:101]
	v_mfma_f32_16x16x32_bf16 v[86:89], v[146:149], v[214:217], v[86:89]
	v_mfma_f32_16x16x32_bf16 v[82:85], v[154:157], v[214:217], v[82:85]
	v_mfma_f32_16x16x32_bf16 v[134:137], v[150:153], v[166:169], v[134:137]
	v_mfma_f32_16x16x32_bf16 v[130:133], v[158:161], v[166:169], v[130:133]
	v_mfma_f32_16x16x32_bf16 v[118:121], v[150:153], v[202:205], v[118:121]
	v_mfma_f32_16x16x32_bf16 v[114:117], v[158:161], v[202:205], v[114:117]
	v_mfma_f32_16x16x32_bf16 v[102:105], v[150:153], v[210:213], v[102:105]
	v_mfma_f32_16x16x32_bf16 v[98:101], v[158:161], v[210:213], v[98:101]
	v_mfma_f32_16x16x32_bf16 v[86:89], v[150:153], v[218:221], v[86:89]
	v_mfma_f32_16x16x32_bf16 v[82:85], v[158:161], v[218:221], v[82:85]
	s_setprio 0
	s_barrier
	s_add_u32 s18, s72, 0x80
	s_addc_u32 s19, s73, 0
	s_add_i32 s93, s93, s25
	ds_read_b128 v[162:165], v223 offset:49152
	ds_read_b128 v[166:169], v223 offset:50176
	ds_read_b128 v[198:201], v223 offset:51200
	ds_read_b128 v[202:205], v223 offset:52224
	ds_read_b128 v[206:209], v223 offset:53248
	ds_read_b128 v[210:213], v223 offset:54272
	ds_read_b128 v[214:217], v223 offset:55296
	ds_read_b128 v[218:221], v223 offset:56320
	s_mov_b32 m0, s93
	v_lshl_add_u64 v[224:225], s[18:19], 0, v[194:195]
	global_load_lds_dwordx4 v[224:225], off
	s_add_i32 m0, s93, 0x2000
	v_lshl_add_u64 v[224:225], s[18:19], 0, v[170:171]
	s_add_u32 s18, s72, 0x40080
	s_addc_u32 s19, s73, 0
	s_add_i32 s72, s94, s25
	global_load_lds_dwordx4 v[224:225], off
	s_mov_b32 m0, s72
	v_lshl_add_u64 v[224:225], s[18:19], 0, v[194:195]
	global_load_lds_dwordx4 v[224:225], off
	v_lshl_add_u64 v[224:225], s[18:19], 0, v[170:171]
	s_add_i32 m0, s72, 0x2000
	s_nop 0
	global_load_lds_dwordx4 v[224:225], off
	s_mov_b32 m0, s82
	v_lshl_add_u64 v[224:225], s[26:27], 0, v[196:197]
	global_load_lds_dwordx4 v[224:225], off
	v_lshl_add_u64 v[224:225], s[26:27], 0, v[172:173]
	s_mov_b32 m0, s83
	s_nop 0
	global_load_lds_dwordx4 v[224:225], off
	s_waitcnt vmcnt(8)
	s_waitcnt lgkmcnt(0)
	s_barrier
	s_setprio 1
	s_waitcnt lgkmcnt(0)
	s_cmp_lg_u32 s100, 0
	s_cbranch_scc1 .Lh13_m1
	v_mfma_f32_16x16x32_bf16 v[62:65], v[66:69], v[162:165], v[62:65]
	v_mfma_f32_16x16x32_bf16 v[58:61], v[74:77], v[162:165], v[58:61]
	v_mfma_f32_16x16x32_bf16 v[46:49], v[66:69], v[198:201], v[46:49]
	v_mfma_f32_16x16x32_bf16 v[42:45], v[74:77], v[198:201], v[42:45]
	v_mfma_f32_16x16x32_bf16 v[30:33], v[66:69], v[206:209], v[30:33]
	v_mfma_f32_16x16x32_bf16 v[26:29], v[74:77], v[206:209], v[26:29]
	v_mfma_f32_16x16x32_bf16 v[14:17], v[66:69], v[214:217], v[14:17]
	v_mfma_f32_16x16x32_bf16 v[10:13], v[74:77], v[214:217], v[10:13]
	v_mfma_f32_16x16x32_bf16 v[62:65], v[70:73], v[166:169], v[62:65]
	v_mfma_f32_16x16x32_bf16 v[58:61], v[78:81], v[166:169], v[58:61]
	v_mfma_f32_16x16x32_bf16 v[46:49], v[70:73], v[202:205], v[46:49]
	v_mfma_f32_16x16x32_bf16 v[42:45], v[78:81], v[202:205], v[42:45]
	v_mfma_f32_16x16x32_bf16 v[30:33], v[70:73], v[210:213], v[30:33]
	v_mfma_f32_16x16x32_bf16 v[26:29], v[78:81], v[210:213], v[26:29]
	v_mfma_f32_16x16x32_bf16 v[14:17], v[70:73], v[218:221], v[14:17]
	v_mfma_f32_16x16x32_bf16 v[10:13], v[78:81], v[218:221], v[10:13]
	v_mfma_f32_16x16x32_bf16 v[54:57], v[146:149], v[162:165], v[54:57]
	v_mfma_f32_16x16x32_bf16 v[50:53], v[154:157], v[162:165], v[50:53]
	v_mfma_f32_16x16x32_bf16 v[38:41], v[146:149], v[198:201], v[38:41]
	v_mfma_f32_16x16x32_bf16 v[34:37], v[154:157], v[198:201], v[34:37]
	v_mfma_f32_16x16x32_bf16 v[22:25], v[146:149], v[206:209], v[22:25]
	v_mfma_f32_16x16x32_bf16 v[18:21], v[154:157], v[206:209], v[18:21]
	v_mfma_f32_16x16x32_bf16 v[6:9], v[146:149], v[214:217], v[6:9]
	v_mfma_f32_16x16x32_bf16 v[2:5], v[154:157], v[214:217], v[2:5]
	v_mfma_f32_16x16x32_bf16 v[54:57], v[150:153], v[166:169], v[54:57]
	v_mfma_f32_16x16x32_bf16 v[50:53], v[158:161], v[166:169], v[50:53]
	v_mfma_f32_16x16x32_bf16 v[38:41], v[150:153], v[202:205], v[38:41]
	v_mfma_f32_16x16x32_bf16 v[34:37], v[158:161], v[202:205], v[34:37]
	v_mfma_f32_16x16x32_bf16 v[22:25], v[150:153], v[210:213], v[22:25]
	v_mfma_f32_16x16x32_bf16 v[18:21], v[158:161], v[210:213], v[18:21]
	v_mfma_f32_16x16x32_bf16 v[6:9], v[150:153], v[218:221], v[6:9]
	v_mfma_f32_16x16x32_bf16 v[2:5], v[158:161], v[218:221], v[2:5]
.Lh13_m1:
	s_setprio 0
	s_barrier
	s_add_u32 vcc_lo, vcc_lo, 0x100
	s_addc_u32 vcc_hi, vcc_hi, 0
	s_add_u32 s90, s90, 0x100
	s_addc_u32 s91, s91, 0
	s_add_u32 s2, s2, 0x100
	s_addc_u32 s3, s3, 0
	s_cmp_ge_i32 s92, s41
	s_mov_b32 s18, s92
	s_cbranch_scc0 .LBB0_691
	s_movk_i32 s90, 0x80
	s_mov_b32 s91, 0x10000
	s_mov_b32 s92, 0x12000
	s_mov_b32 s93, 0x14000
	s_mov_b32 s94, 0x16000
	s_movk_i32 s95, 0x4000
	s_movk_i32 s96, 0x3000
	s_mov_b32 s72, 0x18000

.LBB0_695:
	v_mov_b32_e32 v66, v179
	s_cmp_eq_u32 s100, 2
	s_cselect_b32 vcc_lo, 0x80, 0
	s_lshl_b32 s1, s88, 8
	v_bfe_u32 v0, v66, 6, 2
	v_and_b32_e32 v225, 15, v66
	v_bfe_u32 v224, v66, 4, 2
	v_ashrrev_i32_e32 v66, 2, v66
	v_and_b32_e32 v66, 0xffffffc0, v66
	v_lshl_add_u32 v164, s0, 8, v66
	v_add_u32_e32 v164, vcc_lo, v164
	v_lshlrev_b32_e32 v66, 5, v0
	v_lshlrev_b32_e32 v67, 3, v224
	v_or3_b32 v216, v66, s1, v67
	s_add_i32 s1, s0, -16
	s_lshr_b32 s1, s1, 3
	s_add_i32 s1, s1, 1
	s_cmp_lt_i32 s0, 16
	s_cselect_b32 s0, 0, s1
	s_mul_i32 s19, s0, 0x6000
	s_mul_hi_u32 s18, s0, 0x6000
	s_cselect_b32 s1, s49, s86
	s_cselect_b32 s0, s48, s85
	s_add_u32 s2, s79, s19
	v_ashrrev_i32_e32 v217, 31, v216
	s_addc_u32 s3, s80, s18
	v_lshlrev_b64 v[162:163], 2, v[216:217]
	v_lshl_add_u64 v[154:155], s[2:3], 0, v[162:163]
	s_add_u32 s2, s81, s19
	s_addc_u32 s3, s40, s18
	v_lshl_add_u64 v[156:157], s[30:31], 0, v[162:163]
	v_lshl_add_u64 v[158:159], s[2:3], 0, v[162:163]
	global_load_dwordx4 v[74:77], v[154:155], off offset:16
	global_load_dwordx4 v[78:81], v[154:155], off
	global_load_dwordx4 v[66:69], v[156:157], off offset:16
	global_load_dwordx4 v[70:73], v[156:157], off
	global_load_dwordx4 v[146:149], v[158:159], off offset:16
	global_load_dwordx4 v[150:153], v[158:159], off
	v_or_b32_e32 v198, v164, v225
	v_ashrrev_i32_e32 v199, 31, v198
	v_lshl_add_u64 v[220:221], s[0:1], 0, v[162:163]
	v_or_b32_e32 v218, 16, v198
	v_ashrrev_i32_e32 v219, 31, v218
	v_lshlrev_b64 v[248:249], 10, v[198:199]
	v_lshl_add_u64 v[248:249], v[248:249], 0, v[216:217]
	v_cmp_eq_u32_e32 vcc, 0, v224
	s_waitcnt vmcnt(0)
	v_pk_add_f32 v[152:153], v[152:153], 1.0 op_sel_hi:[1,0]
	v_pk_add_f32 v[150:151], v[150:151], 1.0 op_sel_hi:[1,0]
	v_pk_mul_f32 v[208:209], v[72:73], v[152:153]
	v_pk_mul_f32 v[210:211], v[70:71], v[150:151]
	v_pk_add_f32 v[70:71], v[148:149], 1.0 op_sel_hi:[1,0]
	v_pk_add_f32 v[72:73], v[146:147], 1.0 op_sel_hi:[1,0]
	v_pk_mul_f32 v[212:213], v[68:69], v[70:71]
	v_pk_mul_f32 v[214:215], v[66:67], v[72:73]
	global_load_dwordx4 v[66:69], v[154:155], off offset:528
	global_load_dwordx4 v[70:73], v[154:155], off offset:512
	global_load_dwordx4 v[146:149], v[156:157], off offset:528
	global_load_dwordx4 v[150:153], v[156:157], off offset:512
	s_nop 0
	global_load_dwordx4 v[154:157], v[158:159], off offset:528
	s_nop 0
	global_load_dwordx4 v[158:161], v[158:159], off offset:512
	s_waitcnt vmcnt(0)
	v_pk_add_f32 v[160:161], v[160:161], 1.0 op_sel_hi:[1,0]
	s_nop 0
	v_pk_mul_f32 v[200:201], v[152:153], v[160:161]
	v_pk_add_f32 v[152:153], v[154:155], 1.0 op_sel_hi:[1,0]
	v_pk_add_f32 v[158:159], v[158:159], 1.0 op_sel_hi:[1,0]
	v_pk_mul_f32 v[206:207], v[146:147], v[152:153]
	v_lshlrev_b64 v[146:147], 12, v[198:199]
	v_lshl_add_u64 v[146:147], v[220:221], 0, v[146:147]
	global_load_dwordx4 v[226:229], v[146:147], off offset:16
	global_load_dwordx4 v[244:247], v[146:147], off
	global_load_dwordx4 v[162:165], v[146:147], off offset:528
	global_load_dwordx4 v[166:169], v[146:147], off offset:512
	v_pk_mul_f32 v[202:203], v[150:151], v[158:159]
	v_pk_add_f32 v[150:151], v[156:157], 1.0 op_sel_hi:[1,0]
	v_lshlrev_b64 v[146:147], 12, v[218:219]
	v_pk_mul_f32 v[204:205], v[148:149], v[150:151]
	v_lshl_add_u64 v[150:151], v[220:221], 0, v[146:147]
	global_load_dwordx4 v[154:157], v[150:151], off offset:16
	global_load_dwordx4 v[158:161], v[150:151], off
	global_load_dwordx4 v[146:149], v[150:151], off offset:528
	s_nop 0
	global_load_dwordx4 v[150:153], v[150:151], off offset:512
	s_waitcnt vmcnt(0)
	v_pk_fma_f32 v[144:145], v[144:145], v[76:77], v[228:229]
	v_pk_fma_f32 v[246:247], v[140:141], v[80:81], v[246:247]
	v_pk_fma_f32 v[244:245], v[138:139], v[78:79], v[244:245]
	v_mul_f32_e32 v141, v247, v247
	v_mul_f32_e32 v140, v245, v245
	v_pk_fma_f32 v[142:143], v[142:143], v[74:75], v[226:227]
	v_fmac_f32_e32 v140, v244, v244
	v_fmac_f32_e32 v141, v246, v246
	v_add_f32_e32 v140, v140, v141
	v_mul_f32_e32 v141, v143, v143
	v_mul_f32_e32 v226, v145, v145
	v_fmac_f32_e32 v141, v142, v142
	v_fmac_f32_e32 v226, v144, v144
	v_lshl_add_u64 v[138:139], v[248:249], 2, s[44:45]
	v_add_f32_e32 v141, v141, v226
	global_store_dwordx4 v[138:139], v[244:247], off
	global_store_dwordx4 v[138:139], v[142:145], off offset:16
	v_add_f32_e32 v228, v140, v141
	v_pk_mul_f32 v[140:141], v[210:211], v[244:245]
	v_pk_mul_f32 v[144:145], v[212:213], v[144:145]
	v_pk_mul_f32 v[142:143], v[214:215], v[142:143]
	v_pk_mul_f32 v[226:227], v[208:209], v[246:247]
	v_cvt_pk_bf16_f32 v140, v140, v141
	v_pk_fma_f32 v[136:137], v[136:137], v[72:73], v[168:169]
	v_cvt_pk_bf16_f32 v141, v226, v227
	v_cvt_pk_bf16_f32 v142, v142, v143
	v_cvt_pk_bf16_f32 v143, v144, v145
	v_lshl_add_u64 v[144:145], v[248:249], 1, s[34:35]
	v_pk_fma_f32 v[134:135], v[134:135], v[70:71], v[166:167]
	global_store_dwordx4 v[144:145], v[140:143], off
	v_pk_fma_f32 v[132:133], v[132:133], v[68:69], v[164:165]
	v_pk_fma_f32 v[130:131], v[130:131], v[66:67], v[162:163]
	global_store_dwordx4 v[138:139], v[134:137], off offset:512
	global_store_dwordx4 v[138:139], v[130:133], off offset:528
	v_mul_f32_e32 v138, v135, v135
	v_mul_f32_e32 v139, v137, v137
	v_fmac_f32_e32 v138, v134, v134
	v_fmac_f32_e32 v139, v136, v136
	v_add_f32_e32 v138, v138, v139
	v_mul_f32_e32 v139, v131, v131
	v_mul_f32_e32 v140, v133, v133
	v_fmac_f32_e32 v139, v130, v130
	v_fmac_f32_e32 v140, v132, v132
	v_add_f32_e32 v139, v139, v140
	v_add_f32_e32 v138, v138, v139
	v_pk_mul_f32 v[134:135], v[202:203], v[134:135]
	v_pk_fma_f32 v[128:129], v[128:129], v[80:81], v[160:161]
	v_pk_fma_f32 v[126:127], v[126:127], v[78:79], v[158:159]
	v_add_f32_e32 v142, v228, v138
	v_pk_mul_f32 v[136:137], v[200:201], v[136:137]
	v_pk_mul_f32 v[138:139], v[204:205], v[132:133]
	v_pk_mul_f32 v[132:133], v[206:207], v[130:131]
	v_cvt_pk_bf16_f32 v130, v134, v135
	v_cvt_pk_bf16_f32 v131, v136, v137
	v_mul_f32_e32 v134, v127, v127
	v_mul_f32_e32 v135, v129, v129
	v_cvt_pk_bf16_f32 v132, v132, v133
	v_cvt_pk_bf16_f32 v133, v138, v139
	global_store_dwordx4 v[144:145], v[130:133], off offset:256
	v_pk_fma_f32 v[124:125], v[124:125], v[76:77], v[156:157]
	v_pk_fma_f32 v[122:123], v[122:123], v[74:75], v[154:155]
	v_lshlrev_b64 v[130:131], 10, v[218:219]
	v_fmac_f32_e32 v134, v126, v126
	v_fmac_f32_e32 v135, v128, v128
	v_lshl_add_u64 v[130:131], v[130:131], 0, v[216:217]
	v_add_f32_e32 v134, v134, v135
	v_mul_f32_e32 v135, v123, v123
	v_mul_f32_e32 v136, v125, v125
	v_lshl_add_u64 v[132:133], v[130:131], 2, s[44:45]
	v_fmac_f32_e32 v135, v122, v122
	v_fmac_f32_e32 v136, v124, v124
	global_store_dwordx4 v[132:133], v[126:129], off
	global_store_dwordx4 v[132:133], v[122:125], off offset:16
	v_add_f32_e32 v135, v135, v136
	v_pk_mul_f32 v[126:127], v[210:211], v[126:127]
	v_add_f32_e32 v136, v134, v135
	v_pk_mul_f32 v[128:129], v[208:209], v[128:129]
	v_pk_mul_f32 v[134:135], v[212:213], v[124:125]
	v_pk_mul_f32 v[124:125], v[214:215], v[122:123]
	v_cvt_pk_bf16_f32 v122, v126, v127
	v_cvt_pk_bf16_f32 v123, v128, v129
	v_lshl_add_u64 v[126:127], v[130:131], 1, s[34:35]
	v_pk_fma_f32 v[120:121], v[120:121], v[72:73], v[152:153]
	v_pk_fma_f32 v[118:119], v[118:119], v[70:71], v[150:151]
	v_cvt_pk_bf16_f32 v124, v124, v125
	v_cvt_pk_bf16_f32 v125, v134, v135
	global_store_dwordx4 v[126:127], v[122:125], off
	v_pk_fma_f32 v[116:117], v[116:117], v[68:69], v[148:149]
	v_pk_fma_f32 v[114:115], v[114:115], v[66:67], v[146:147]
	v_mul_f32_e32 v122, v119, v119
	v_mul_f32_e32 v123, v121, v121
	v_fmac_f32_e32 v122, v118, v118
	v_fmac_f32_e32 v123, v120, v120
	v_add_f32_e32 v122, v122, v123
	v_mul_f32_e32 v123, v115, v115
	v_mul_f32_e32 v124, v117, v117
	v_fmac_f32_e32 v123, v114, v114
	v_fmac_f32_e32 v124, v116, v116
	v_add_f32_e32 v123, v123, v124
	v_add_f32_e32 v122, v122, v123
	v_or_b32_e32 v138, 32, v198
	global_store_dwordx4 v[132:133], v[118:121], off offset:512
	global_store_dwordx4 v[132:133], v[114:117], off offset:528
	v_add_f32_e32 v143, v136, v122
	v_pk_mul_f32 v[120:121], v[200:201], v[120:121]
	v_pk_mul_f32 v[118:119], v[202:203], v[118:119]
	v_pk_mul_f32 v[122:123], v[204:205], v[116:117]
	v_pk_mul_f32 v[116:117], v[206:207], v[114:115]
	v_cvt_pk_bf16_f32 v114, v118, v119
	v_cvt_pk_bf16_f32 v115, v120, v121
	v_ashrrev_i32_e32 v139, 31, v138
	v_cvt_pk_bf16_f32 v116, v116, v117
	v_cvt_pk_bf16_f32 v117, v122, v123
	global_store_dwordx4 v[126:127], v[114:117], off offset:256
	v_or_b32_e32 v140, 48, v198
	v_ashrrev_i32_e32 v141, 31, v140
	v_lshlrev_b64 v[114:115], 12, v[138:139]
	v_lshl_add_u64 v[114:115], v[220:221], 0, v[114:115]
	global_load_dwordx4 v[144:147], v[114:115], off offset:16
	global_load_dwordx4 v[148:151], v[114:115], off
	global_load_dwordx4 v[130:133], v[114:115], off offset:528
	global_load_dwordx4 v[134:137], v[114:115], off offset:512
	v_lshlrev_b64 v[114:115], 12, v[140:141]
	v_lshl_add_u64 v[118:119], v[220:221], 0, v[114:115]
	global_load_dwordx4 v[122:125], v[118:119], off offset:16
	global_load_dwordx4 v[126:129], v[118:119], off
	global_load_dwordx4 v[114:117], v[118:119], off offset:528
	s_nop 0
	global_load_dwordx4 v[118:121], v[118:119], off offset:512
	v_lshlrev_b64 v[152:153], 10, v[138:139]
	v_lshl_add_u64 v[152:153], v[152:153], 0, v[216:217]
	s_waitcnt vmcnt(0)
	v_pk_fma_f32 v[108:109], v[108:109], v[76:77], v[146:147]
	v_pk_fma_f32 v[112:113], v[112:113], v[80:81], v[150:151]
	v_pk_fma_f32 v[110:111], v[110:111], v[78:79], v[148:149]
	v_mul_f32_e32 v147, v113, v113
	v_mul_f32_e32 v146, v111, v111
	v_pk_fma_f32 v[106:107], v[106:107], v[74:75], v[144:145]
	v_fmac_f32_e32 v146, v110, v110
	v_fmac_f32_e32 v147, v112, v112
	v_add_f32_e32 v146, v146, v147
	v_mul_f32_e32 v147, v107, v107
	v_mul_f32_e32 v148, v109, v109
	v_lshl_add_u64 v[144:145], v[152:153], 2, s[44:45]
	v_fmac_f32_e32 v147, v106, v106
	v_fmac_f32_e32 v148, v108, v108
	global_store_dwordx4 v[144:145], v[110:113], off
	global_store_dwordx4 v[144:145], v[106:109], off offset:16
	v_add_f32_e32 v147, v147, v148
	v_pk_mul_f32 v[110:111], v[210:211], v[110:111]
	v_add_f32_e32 v148, v146, v147
	v_pk_mul_f32 v[112:113], v[208:209], v[112:113]
	v_pk_mul_f32 v[146:147], v[212:213], v[108:109]
	v_pk_mul_f32 v[108:109], v[214:215], v[106:107]
	v_cvt_pk_bf16_f32 v106, v110, v111
	v_cvt_pk_bf16_f32 v107, v112, v113
	v_lshl_add_u64 v[110:111], v[152:153], 1, s[34:35]
	v_pk_fma_f32 v[104:105], v[104:105], v[72:73], v[136:137]
	v_pk_fma_f32 v[102:103], v[102:103], v[70:71], v[134:135]
	v_cvt_pk_bf16_f32 v108, v108, v109
	v_cvt_pk_bf16_f32 v109, v146, v147
	global_store_dwordx4 v[110:111], v[106:109], off
	v_pk_fma_f32 v[100:101], v[100:101], v[68:69], v[132:133]
	v_pk_fma_f32 v[98:99], v[98:99], v[66:67], v[130:131]
	v_mul_f32_e32 v106, v103, v103
	v_mul_f32_e32 v107, v105, v105
	v_fmac_f32_e32 v106, v102, v102
	v_fmac_f32_e32 v107, v104, v104
	v_add_f32_e32 v106, v106, v107
	v_mul_f32_e32 v107, v99, v99
	v_mul_f32_e32 v108, v101, v101
	v_fmac_f32_e32 v107, v98, v98
	v_fmac_f32_e32 v108, v100, v100
	v_add_f32_e32 v107, v107, v108
	global_store_dwordx4 v[144:145], v[102:105], off offset:512
	global_store_dwordx4 v[144:145], v[98:101], off offset:528
	v_add_f32_e32 v106, v106, v107
	v_pk_mul_f32 v[102:103], v[202:203], v[102:103]
	v_pk_fma_f32 v[96:97], v[96:97], v[80:81], v[128:129]
	v_pk_fma_f32 v[94:95], v[94:95], v[78:79], v[126:127]
	v_add_f32_e32 v130, v148, v106
	v_pk_mul_f32 v[104:105], v[200:201], v[104:105]
	v_pk_mul_f32 v[106:107], v[204:205], v[100:101]
	v_pk_mul_f32 v[100:101], v[206:207], v[98:99]
	v_cvt_pk_bf16_f32 v98, v102, v103
	v_cvt_pk_bf16_f32 v99, v104, v105
	v_mul_f32_e32 v102, v95, v95
	v_mul_f32_e32 v103, v97, v97
	v_cvt_pk_bf16_f32 v100, v100, v101
	v_cvt_pk_bf16_f32 v101, v106, v107
	global_store_dwordx4 v[110:111], v[98:101], off offset:256
	v_pk_fma_f32 v[92:93], v[92:93], v[76:77], v[124:125]
	v_pk_fma_f32 v[90:91], v[90:91], v[74:75], v[122:123]
	v_lshlrev_b64 v[98:99], 10, v[140:141]
	v_fmac_f32_e32 v102, v94, v94
	v_fmac_f32_e32 v103, v96, v96
	v_lshl_add_u64 v[98:99], v[98:99], 0, v[216:217]
	v_add_f32_e32 v102, v102, v103
	v_mul_f32_e32 v103, v91, v91
	v_mul_f32_e32 v104, v93, v93
	v_lshl_add_u64 v[100:101], v[98:99], 2, s[44:45]
	v_fmac_f32_e32 v103, v90, v90
	v_fmac_f32_e32 v104, v92, v92
	global_store_dwordx4 v[100:101], v[94:97], off
	global_store_dwordx4 v[100:101], v[90:93], off offset:16
	v_add_f32_e32 v103, v103, v104
	v_pk_mul_f32 v[94:95], v[210:211], v[94:95]
	v_add_f32_e32 v104, v102, v103
	v_pk_mul_f32 v[96:97], v[208:209], v[96:97]
	v_pk_mul_f32 v[102:103], v[212:213], v[92:93]
	v_pk_mul_f32 v[92:93], v[214:215], v[90:91]
	v_cvt_pk_bf16_f32 v90, v94, v95
	v_cvt_pk_bf16_f32 v91, v96, v97
	v_lshl_add_u64 v[94:95], v[98:99], 1, s[34:35]
	v_pk_fma_f32 v[88:89], v[88:89], v[72:73], v[120:121]
	v_pk_fma_f32 v[86:87], v[86:87], v[70:71], v[118:119]
	v_cvt_pk_bf16_f32 v92, v92, v93
	v_cvt_pk_bf16_f32 v93, v102, v103
	global_store_dwordx4 v[94:95], v[90:93], off
	v_pk_fma_f32 v[84:85], v[84:85], v[68:69], v[116:117]
	v_pk_fma_f32 v[82:83], v[82:83], v[66:67], v[114:115]
	v_mul_f32_e32 v90, v87, v87
	v_mul_f32_e32 v91, v89, v89
	v_fmac_f32_e32 v90, v86, v86
	v_fmac_f32_e32 v91, v88, v88
	v_add_f32_e32 v90, v90, v91
	v_mul_f32_e32 v91, v83, v83
	v_mul_f32_e32 v92, v85, v85
	v_fmac_f32_e32 v91, v82, v82
	v_fmac_f32_e32 v92, v84, v84
	v_add_f32_e32 v91, v91, v92
	v_add_f32_e32 v90, v90, v91
	v_add_u32_e32 v114, 0x80, v198
	global_store_dwordx4 v[100:101], v[86:89], off offset:512
	global_store_dwordx4 v[100:101], v[82:85], off offset:528
	v_add_f32_e32 v118, v104, v90
	v_pk_mul_f32 v[88:89], v[200:201], v[88:89]
	v_pk_mul_f32 v[86:87], v[202:203], v[86:87]
	v_pk_mul_f32 v[90:91], v[204:205], v[84:85]
	v_pk_mul_f32 v[84:85], v[206:207], v[82:83]
	v_cvt_pk_bf16_f32 v82, v86, v87
	v_cvt_pk_bf16_f32 v83, v88, v89
	v_ashrrev_i32_e32 v115, 31, v114
	v_cvt_pk_bf16_f32 v84, v84, v85
	v_cvt_pk_bf16_f32 v85, v90, v91
	global_store_dwordx4 v[94:95], v[82:85], off offset:256
	s_cmp_lg_u32 s100, 0
	s_cbranch_scc0 .Lh13_f
	v_lshlrev_b32_e32 v9, 6, v224
	v_lshlrev_b32_e32 v10, 2, v225
	v_bitop3_b32 v11, v9, 64, v10 bitop3:0x36
	s_branch .Lh13_ss
.Lh13_f:
	v_add_u32_e32 v116, 0x90, v198
	v_ashrrev_i32_e32 v117, 31, v116
	v_lshlrev_b64 v[82:83], 12, v[114:115]
	v_lshl_add_u64 v[82:83], v[220:221], 0, v[82:83]
	global_load_dwordx4 v[106:109], v[82:83], off offset:16
	global_load_dwordx4 v[110:113], v[82:83], off
	global_load_dwordx4 v[98:101], v[82:83], off offset:528
	global_load_dwordx4 v[102:105], v[82:83], off offset:512
	v_lshlrev_b64 v[82:83], 12, v[116:117]
	v_lshl_add_u64 v[86:87], v[220:221], 0, v[82:83]
	global_load_dwordx4 v[90:93], v[86:87], off offset:16
	global_load_dwordx4 v[94:97], v[86:87], off
	global_load_dwordx4 v[82:85], v[86:87], off offset:528
	s_nop 0
	global_load_dwordx4 v[86:89], v[86:87], off offset:512
	v_lshlrev_b64 v[120:121], 10, v[114:115]
	v_lshl_add_u64 v[120:121], v[120:121], 0, v[216:217]
	s_waitcnt vmcnt(0)
	v_pk_fma_f32 v[60:61], v[60:61], v[76:77], v[108:109]
	v_pk_fma_f32 v[64:65], v[64:65], v[80:81], v[112:113]
	v_pk_fma_f32 v[62:63], v[62:63], v[78:79], v[110:111]
	v_mul_f32_e32 v109, v65, v65
	v_mul_f32_e32 v108, v63, v63
	v_pk_fma_f32 v[58:59], v[58:59], v[74:75], v[106:107]
	v_fmac_f32_e32 v108, v62, v62
	v_fmac_f32_e32 v109, v64, v64
	v_add_f32_e32 v108, v108, v109
	v_mul_f32_e32 v109, v59, v59
	v_mul_f32_e32 v110, v61, v61
	v_lshl_add_u64 v[106:107], v[120:121], 2, s[44:45]
	v_fmac_f32_e32 v109, v58, v58
	v_fmac_f32_e32 v110, v60, v60
	global_store_dwordx4 v[106:107], v[62:65], off
	global_store_dwordx4 v[106:107], v[58:61], off offset:16
	v_add_f32_e32 v109, v109, v110
	v_pk_mul_f32 v[62:63], v[210:211], v[62:63]
	v_add_f32_e32 v110, v108, v109
	v_pk_mul_f32 v[64:65], v[208:209], v[64:65]
	v_pk_mul_f32 v[108:109], v[212:213], v[60:61]
	v_pk_mul_f32 v[60:61], v[214:215], v[58:59]
	v_cvt_pk_bf16_f32 v58, v62, v63
	v_cvt_pk_bf16_f32 v59, v64, v65
	v_lshl_add_u64 v[62:63], v[120:121], 1, s[34:35]
	v_pk_fma_f32 v[56:57], v[56:57], v[72:73], v[104:105]
	v_pk_fma_f32 v[54:55], v[54:55], v[70:71], v[102:103]
	v_cvt_pk_bf16_f32 v60, v60, v61
	v_cvt_pk_bf16_f32 v61, v108, v109
	global_store_dwordx4 v[62:63], v[58:61], off
	v_pk_fma_f32 v[48:49], v[48:49], v[80:81], v[96:97]
	v_pk_fma_f32 v[46:47], v[46:47], v[78:79], v[94:95]
	v_pk_fma_f32 v[58:59], v[50:51], v[66:67], v[98:99]
	v_mul_f32_e32 v50, v55, v55
	v_mul_f32_e32 v51, v57, v57
	v_pk_fma_f32 v[60:61], v[52:53], v[68:69], v[100:101]
	v_fmac_f32_e32 v50, v54, v54
	v_fmac_f32_e32 v51, v56, v56
	v_add_f32_e32 v50, v50, v51
	v_mul_f32_e32 v51, v59, v59
	v_mul_f32_e32 v52, v61, v61
	v_fmac_f32_e32 v51, v58, v58
	v_fmac_f32_e32 v52, v60, v60
	global_store_dwordx4 v[106:107], v[54:57], off offset:512
	global_store_dwordx4 v[106:107], v[58:61], off offset:528
	v_add_f32_e32 v51, v51, v52
	v_pk_mul_f32 v[56:57], v[200:201], v[56:57]
	v_pk_mul_f32 v[52:53], v[202:203], v[54:55]
	v_add_f32_e32 v50, v50, v51
	v_pk_mul_f32 v[54:55], v[206:207], v[58:59]
	v_cvt_pk_bf16_f32 v52, v52, v53
	v_cvt_pk_bf16_f32 v53, v56, v57
	v_mul_f32_e32 v51, v47, v47
	v_mul_f32_e32 v56, v49, v49
	v_pk_mul_f32 v[60:61], v[204:205], v[60:61]
	v_cvt_pk_bf16_f32 v54, v54, v55
	v_pk_fma_f32 v[44:45], v[44:45], v[76:77], v[92:93]
	v_cvt_pk_bf16_f32 v55, v60, v61
	global_store_dwordx4 v[62:63], v[52:55], off offset:256
	v_pk_fma_f32 v[42:43], v[42:43], v[74:75], v[90:91]
	v_fmac_f32_e32 v51, v46, v46
	v_lshlrev_b64 v[52:53], 10, v[116:117]
	v_fmac_f32_e32 v56, v48, v48
	v_lshl_add_u64 v[52:53], v[52:53], 0, v[216:217]
	v_add_f32_e32 v51, v51, v56
	v_mul_f32_e32 v56, v43, v43
	v_mul_f32_e32 v57, v45, v45
	v_lshl_add_u64 v[54:55], v[52:53], 2, s[44:45]
	v_fmac_f32_e32 v56, v42, v42
	v_fmac_f32_e32 v57, v44, v44
	global_store_dwordx4 v[54:55], v[46:49], off
	global_store_dwordx4 v[54:55], v[42:45], off offset:16
	v_add_f32_e32 v56, v56, v57
	v_pk_mul_f32 v[46:47], v[210:211], v[46:47]
	v_add_f32_e32 v51, v51, v56
	v_pk_mul_f32 v[48:49], v[208:209], v[48:49]
	v_pk_mul_f32 v[56:57], v[212:213], v[44:45]
	v_pk_mul_f32 v[44:45], v[214:215], v[42:43]
	v_cvt_pk_bf16_f32 v42, v46, v47
	v_cvt_pk_bf16_f32 v43, v48, v49
	v_lshl_add_u64 v[46:47], v[52:53], 1, s[34:35]
	v_pk_fma_f32 v[40:41], v[40:41], v[72:73], v[88:89]
	v_pk_fma_f32 v[38:39], v[38:39], v[70:71], v[86:87]
	v_cvt_pk_bf16_f32 v44, v44, v45
	v_cvt_pk_bf16_f32 v45, v56, v57
	global_store_dwordx4 v[46:47], v[42:45], off
	v_pk_fma_f32 v[36:37], v[36:37], v[68:69], v[84:85]
	v_pk_fma_f32 v[34:35], v[34:35], v[66:67], v[82:83]
	v_mul_f32_e32 v42, v39, v39
	v_mul_f32_e32 v43, v41, v41
	v_fmac_f32_e32 v42, v38, v38
	v_fmac_f32_e32 v43, v40, v40
	v_add_f32_e32 v42, v42, v43
	v_mul_f32_e32 v43, v35, v35
	v_mul_f32_e32 v44, v37, v37
	v_fmac_f32_e32 v43, v34, v34
	v_fmac_f32_e32 v44, v36, v36
	v_add_f32_e32 v43, v43, v44
	v_add_f32_e32 v42, v42, v43
	global_store_dwordx4 v[54:55], v[38:41], off offset:512
	global_store_dwordx4 v[54:55], v[34:37], off offset:528
	v_add_f32_e32 v51, v51, v42
	v_pk_mul_f32 v[42:43], v[204:205], v[36:37]
	v_pk_mul_f32 v[36:37], v[206:207], v[34:35]
	v_pk_mul_f32 v[40:41], v[200:201], v[40:41]
	v_pk_mul_f32 v[38:39], v[202:203], v[38:39]
	v_add_f32_e32 v50, v110, v50
	v_cvt_pk_bf16_f32 v34, v38, v39
	v_cvt_pk_bf16_f32 v35, v40, v41
	v_cvt_pk_bf16_f32 v36, v36, v37
	v_cvt_pk_bf16_f32 v37, v42, v43
	global_store_dwordx4 v[46:47], v[34:37], off offset:256
	v_add_u32_e32 v46, 0xa0, v198
	v_ashrrev_i32_e32 v47, 31, v46
	v_lshlrev_b64 v[34:35], 12, v[46:47]
	v_lshl_add_u64 v[48:49], v[220:221], 0, v[34:35]
	global_load_dwordx4 v[38:41], v[48:49], off offset:16
	global_load_dwordx4 v[42:45], v[48:49], off
	global_load_dwordx4 v[34:37], v[48:49], off offset:528
	global_load_dwordx4 v[52:55], v[48:49], off offset:512
	v_add_u32_e32 v48, 0xb0, v198
	v_ashrrev_i32_e32 v49, 31, v48
	v_lshlrev_b64 v[56:57], 12, v[48:49]
	v_lshl_add_u64 v[64:65], v[220:221], 0, v[56:57]
	global_load_dwordx4 v[56:59], v[64:65], off offset:16
	global_load_dwordx4 v[60:63], v[64:65], off
	global_load_dwordx4 v[82:85], v[64:65], off offset:528
	global_load_dwordx4 v[86:89], v[64:65], off offset:512
	v_lshlrev_b64 v[64:65], 10, v[46:47]
	v_lshl_add_u64 v[64:65], v[64:65], 0, v[216:217]
	s_waitcnt vmcnt(0)
	v_pk_fma_f32 v[28:29], v[28:29], v[76:77], v[40:41]
	v_pk_fma_f32 v[32:33], v[32:33], v[80:81], v[44:45]
	v_pk_fma_f32 v[30:31], v[30:31], v[78:79], v[42:43]
	v_mul_f32_e32 v41, v33, v33
	v_mul_f32_e32 v40, v31, v31
	v_pk_fma_f32 v[26:27], v[26:27], v[74:75], v[38:39]
	v_fmac_f32_e32 v40, v30, v30
	v_fmac_f32_e32 v41, v32, v32
	v_add_f32_e32 v40, v40, v41
	v_mul_f32_e32 v41, v27, v27
	v_mul_f32_e32 v42, v29, v29
	v_lshl_add_u64 v[38:39], v[64:65], 2, s[44:45]
	v_fmac_f32_e32 v41, v26, v26
	v_fmac_f32_e32 v42, v28, v28
	global_store_dwordx4 v[38:39], v[30:33], off
	global_store_dwordx4 v[38:39], v[26:29], off offset:16
	v_add_f32_e32 v41, v41, v42
	v_pk_mul_f32 v[30:31], v[210:211], v[30:31]
	v_add_f32_e32 v42, v40, v41
	v_pk_mul_f32 v[32:33], v[208:209], v[32:33]
	v_pk_mul_f32 v[40:41], v[212:213], v[28:29]
	v_pk_mul_f32 v[28:29], v[214:215], v[26:27]
	v_cvt_pk_bf16_f32 v26, v30, v31
	v_cvt_pk_bf16_f32 v27, v32, v33
	v_lshl_add_u64 v[30:31], v[64:65], 1, s[34:35]
	v_pk_fma_f32 v[24:25], v[24:25], v[72:73], v[54:55]
	v_pk_fma_f32 v[22:23], v[22:23], v[70:71], v[52:53]
	v_cvt_pk_bf16_f32 v28, v28, v29
	v_cvt_pk_bf16_f32 v29, v40, v41
	global_store_dwordx4 v[30:31], v[26:29], off
	v_pk_fma_f32 v[20:21], v[20:21], v[68:69], v[36:37]
	v_pk_fma_f32 v[18:19], v[18:19], v[66:67], v[34:35]
	v_mul_f32_e32 v26, v23, v23
	v_mul_f32_e32 v27, v25, v25
	v_fmac_f32_e32 v26, v22, v22
	v_fmac_f32_e32 v27, v24, v24
	v_add_f32_e32 v26, v26, v27
	v_mul_f32_e32 v27, v19, v19
	v_mul_f32_e32 v28, v21, v21
	v_fmac_f32_e32 v27, v18, v18
	v_fmac_f32_e32 v28, v20, v20
	v_add_f32_e32 v27, v27, v28
	global_store_dwordx4 v[38:39], v[22:25], off offset:512
	global_store_dwordx4 v[38:39], v[18:21], off offset:528
	v_add_f32_e32 v26, v26, v27
	v_pk_mul_f32 v[22:23], v[202:203], v[22:23]
	v_pk_fma_f32 v[16:17], v[16:17], v[80:81], v[62:63]
	v_pk_fma_f32 v[14:15], v[14:15], v[78:79], v[60:61]
	v_add_f32_e32 v28, v42, v26
	v_pk_mul_f32 v[24:25], v[200:201], v[24:25]
	v_pk_mul_f32 v[26:27], v[204:205], v[20:21]
	v_pk_mul_f32 v[20:21], v[206:207], v[18:19]
	v_cvt_pk_bf16_f32 v18, v22, v23
	v_cvt_pk_bf16_f32 v19, v24, v25
	v_mul_f32_e32 v22, v15, v15
	v_mul_f32_e32 v23, v17, v17
	v_cvt_pk_bf16_f32 v20, v20, v21
	v_cvt_pk_bf16_f32 v21, v26, v27
	global_store_dwordx4 v[30:31], v[18:21], off offset:256
	v_pk_fma_f32 v[12:13], v[12:13], v[76:77], v[58:59]
	v_pk_fma_f32 v[10:11], v[10:11], v[74:75], v[56:57]
	v_lshlrev_b64 v[18:19], 10, v[48:49]
	v_fmac_f32_e32 v22, v14, v14
	v_fmac_f32_e32 v23, v16, v16
	v_lshl_add_u64 v[18:19], v[18:19], 0, v[216:217]
	v_add_f32_e32 v22, v22, v23
	v_mul_f32_e32 v23, v11, v11
	v_mul_f32_e32 v24, v13, v13
	v_lshl_add_u64 v[20:21], v[18:19], 2, s[44:45]
	v_fmac_f32_e32 v23, v10, v10
	v_fmac_f32_e32 v24, v12, v12
	global_store_dwordx4 v[20:21], v[14:17], off
	global_store_dwordx4 v[20:21], v[10:13], off offset:16
	v_add_f32_e32 v23, v23, v24
	v_pk_mul_f32 v[14:15], v[210:211], v[14:15]
	v_add_f32_e32 v24, v22, v23
	v_pk_mul_f32 v[16:17], v[208:209], v[16:17]
	v_pk_mul_f32 v[22:23], v[212:213], v[12:13]
	v_pk_mul_f32 v[12:13], v[214:215], v[10:11]
	v_cvt_pk_bf16_f32 v10, v14, v15
	v_cvt_pk_bf16_f32 v11, v16, v17
	v_lshl_add_u64 v[14:15], v[18:19], 1, s[34:35]
	v_pk_fma_f32 v[8:9], v[8:9], v[72:73], v[88:89]
	v_pk_fma_f32 v[6:7], v[6:7], v[70:71], v[86:87]
	v_cvt_pk_bf16_f32 v12, v12, v13
	v_cvt_pk_bf16_f32 v13, v22, v23
	global_store_dwordx4 v[14:15], v[10:13], off
	v_pk_fma_f32 v[4:5], v[4:5], v[68:69], v[84:85]
	v_pk_fma_f32 v[2:3], v[2:3], v[66:67], v[82:83]
	v_mul_f32_e32 v10, v7, v7
	v_mul_f32_e32 v11, v9, v9
	v_fmac_f32_e32 v10, v6, v6
	v_fmac_f32_e32 v11, v8, v8
	v_add_f32_e32 v10, v10, v11
	v_mul_f32_e32 v11, v3, v3
	v_mul_f32_e32 v12, v5, v5
	v_fmac_f32_e32 v11, v2, v2
	v_fmac_f32_e32 v12, v4, v4
	v_add_f32_e32 v11, v11, v12
	v_add_f32_e32 v10, v10, v11
	global_store_dwordx4 v[20:21], v[6:9], off offset:512
	global_store_dwordx4 v[20:21], v[2:5], off offset:528
	v_add_f32_e32 v12, v24, v10
	v_pk_mul_f32 v[8:9], v[200:201], v[8:9]
	v_pk_mul_f32 v[10:11], v[204:205], v[4:5]
	v_pk_mul_f32 v[4:5], v[206:207], v[2:3]
	v_pk_mul_f32 v[6:7], v[202:203], v[6:7]
	s_nop 0
	v_cvt_pk_bf16_f32 v2, v6, v7
	v_cvt_pk_bf16_f32 v3, v8, v9
	v_cvt_pk_bf16_f32 v4, v4, v5
	v_cvt_pk_bf16_f32 v5, v10, v11
	v_lshlrev_b32_e32 v9, 6, v224
	v_lshlrev_b32_e32 v10, 2, v225
	v_bitop3_b32 v11, v9, 64, v10 bitop3:0x36
	global_store_dwordx4 v[14:15], v[2:5], off offset:256
.Lh13_ss:
	ds_bpermute_b32 v2, v11, v142
	ds_bpermute_b32 v3, v11, v143
	ds_bpermute_b32 v4, v11, v130
	ds_bpermute_b32 v5, v11, v118
	ds_bpermute_b32 v6, v11, v50
	ds_bpermute_b32 v7, v11, v51
	ds_bpermute_b32 v8, v11, v28
	ds_bpermute_b32 v11, v11, v12
	s_waitcnt lgkmcnt(0)
	v_add_f32_e32 v2, v142, v2
	v_add_f32_e32 v3, v143, v3
	v_add_f32_e32 v4, v130, v4
	v_add_f32_e32 v5, v118, v5
	v_add_f32_e32 v6, v50, v6
	v_add_f32_e32 v7, v51, v7
	v_add_f32_e32 v8, v28, v8
	v_add_f32_e32 v12, v12, v11
	v_bitop3_b32 v17, v9, s90, v10 bitop3:0x36
	ds_bpermute_b32 v9, v17, v2
	ds_bpermute_b32 v10, v17, v3
	ds_bpermute_b32 v11, v17, v4
	ds_bpermute_b32 v13, v17, v5
	ds_bpermute_b32 v14, v17, v6
	ds_bpermute_b32 v15, v17, v7
	ds_bpermute_b32 v16, v17, v8
	ds_bpermute_b32 v17, v17, v12
	s_and_saveexec_b64 s[0:1], vcc
	s_cbranch_execz .LBB0_697
	s_lshl_b32 s2, s88, 2
	s_ashr_i32 s3, s2, 31
	s_lshl_b64 s[2:3], s[2:3], 2
	s_add_u32 s2, s71, s2
	s_addc_u32 s3, s78, s3
	v_lshlrev_b32_e32 v0, 2, v0
	s_waitcnt lgkmcnt(4)
	v_add_f32_e32 v13, v5, v13
	v_add_f32_e32 v11, v4, v11
	v_add_f32_e32 v10, v3, v10
	v_add_f32_e32 v9, v2, v9
	v_lshl_add_u64 v[2:3], s[2:3], 0, v[0:1]
	v_lshlrev_b64 v[4:5], 6, v[198:199]
	v_lshl_add_u64 v[4:5], v[2:3], 0, v[4:5]
	global_store_dword v[4:5], v9, off
	v_lshlrev_b64 v[4:5], 6, v[218:219]
	v_lshl_add_u64 v[4:5], v[2:3], 0, v[4:5]
	global_store_dword v[4:5], v10, off
	v_lshlrev_b64 v[4:5], 6, v[138:139]
	v_lshl_add_u64 v[4:5], v[2:3], 0, v[4:5]
	global_store_dword v[4:5], v11, off
	v_lshlrev_b64 v[4:5], 6, v[140:141]
	v_lshl_add_u64 v[4:5], v[2:3], 0, v[4:5]
	global_store_dword v[4:5], v13, off
	s_cmp_lg_u32 s100, 0
	s_cbranch_scc0 .Lh13_g
	s_waitcnt lgkmcnt(0)
	s_branch .LBB0_697
.Lh13_g:
	v_lshlrev_b64 v[4:5], 6, v[114:115]
	s_waitcnt lgkmcnt(3)
	v_add_f32_e32 v6, v6, v14
	v_lshl_add_u64 v[4:5], v[2:3], 0, v[4:5]
	global_store_dword v[4:5], v6, off
	v_lshlrev_b64 v[4:5], 6, v[116:117]
	s_waitcnt lgkmcnt(2)
	v_add_f32_e32 v7, v7, v15
	v_lshl_add_u64 v[4:5], v[2:3], 0, v[4:5]
	global_store_dword v[4:5], v7, off
	v_lshlrev_b64 v[4:5], 6, v[46:47]
	s_waitcnt lgkmcnt(1)
	v_add_f32_e32 v8, v8, v16
	v_lshl_add_u64 v[4:5], v[2:3], 0, v[4:5]
	global_store_dword v[4:5], v8, off
	v_lshlrev_b64 v[4:5], 6, v[48:49]
	s_waitcnt lgkmcnt(0)
	v_add_f32_e32 v12, v12, v17
	v_lshl_add_u64 v[2:3], v[2:3], 0, v[4:5]
	global_store_dword v[2:3], v12, off

.LBB0_1308:
	v_readlane_b32 s30, v255, 31
	v_readlane_b32 s31, v255, 32
	s_mov_b32 s57, s31
	s_mul_i32 s56, s8, 0xd800
	s_lshl_b64 s[30:31], s[56:57], 2
	s_add_u32 s1, s46, s30
	s_addc_u32 s55, s47, s31
	s_add_u32 s71, s46, 0x5e00000
	s_addc_u32 s72, s47, 0
	s_add_u32 s73, s1, 0x2000
	s_mov_b32 s31, s57
	s_addc_u32 s78, s55, 0
	s_lshl_b32 s56, s8, 10
	v_writelane_b32 v255, s30, 31
	v_mov_b32_e32 v195, v1
	s_waitcnt vmcnt(2)
	s_barrier
	v_writelane_b32 v255, s31, 32
	s_lshl_b64 s[30:31], s[56:57], 2
	s_waitcnt lgkmcnt(0)
	s_add_u32 s30, s18, s30
	s_addc_u32 s31, s19, s31
	s_add_u32 s79, s1, 0x4000
	s_addc_u32 s80, s55, 0
	s_ashr_i32 s1, s54, 31
	s_lshr_b32 s1, s1, 26
	s_add_i32 s1, s54, s1
	s_lshl_b32 s18, s34, 12
	s_ashr_i32 s84, s1, 6
	s_lshl_b32 s1, s35, 13
	s_and_b32 s55, s18, 0x3000
	s_add_u32 s34, s46, 0x6000000
	s_addc_u32 s35, s47, 0
	s_add_u32 s18, s2, 0x80
	s_addc_u32 s19, s3, 0
	s_add_i32 m0, s67, 0x18000
	v_lshl_add_u64 v[2:3], s[18:19], 0, v[194:195]
	v_mov_b32_e32 v171, v1
	global_load_lds_dwordx4 v[2:3], off
	s_add_i32 m0, s67, 0x1a000
	v_lshl_add_u64 v[2:3], s[18:19], 0, v[170:171]
	s_add_u32 s18, s26, 0x80
	v_mov_b32_e32 v197, v1
	s_addc_u32 s19, s27, 0
	s_add_i32 s82, s67, 0x8000
	v_mov_b32_e32 v173, v1
	global_load_lds_dwordx4 v[2:3], off
	s_mov_b32 m0, s82
	v_lshl_add_u64 v[2:3], s[18:19], 0, v[196:197]
	s_add_i32 s83, s67, 0xa000
	global_load_lds_dwordx4 v[2:3], off
	v_lshl_add_u64 v[2:3], s[18:19], 0, v[172:173]
	s_add_u32 s18, s50, 0x80
	s_mov_b32 m0, s83
	s_addc_u32 s19, s51, 0
	global_load_lds_dwordx4 v[2:3], off
	s_add_i32 m0, s67, 0x1c000
	v_lshl_add_u64 v[2:3], s[18:19], 0, v[194:195]
	global_load_lds_dwordx4 v[2:3], off
	v_lshl_add_u64 v[2:3], s[18:19], 0, v[170:171]
	s_add_i32 m0, s67, 0x1e000
	s_cmp_gt_i32 s54, 63
	global_load_lds_dwordx4 v[2:3], off
	v_and_b32_e32 v2, 15, v0
	v_and_b32_e32 v3, 48, v0
	v_lshlrev_b32_e32 v2, 6, v2
	v_lshlrev_b32_e32 v0, 2, v0
	s_cselect_b64 s[46:47], -1, 0
	s_add_i32 s81, s84, -2
	v_or_b32_e32 v4, v2, v3
	v_and_b32_e32 v0, 32, v0
	s_waitcnt vmcnt(6)
	s_cmpk_lt_u32 s41, 0x100
	v_bitop3_b32 v2, v2, v0, v3 bitop3:0x36
	v_bitop3_b32 v0, v4, s1, v0 bitop3:0xde
	s_cselect_b64 s[50:51], -1, 0
	s_add_u32 s85, s36, 0xff000000
	s_sext_i32_i8 s88, s40
	v_or_b32_e32 v222, s55, v2
	s_addc_u32 s86, s37, -1
	s_mov_b32 s87, 0
	s_mov_b32 s100, 0
	s_mov_b32 s101, 0
	v_add_u32_e32 v223, 0, v0
	s_barrier
	s_branch .LBB0_1311

.LBB0_1310:
	s_mov_b32 s100, s101
	s_andn2_b64 vcc, exec, s[0:1]
	s_mov_b32 s88, s36
	s_mov_b32 s0, s54
	s_mov_b64 s[2:3], s[60:61]
	s_mov_b64 s[26:27], s[56:57]
	s_cbranch_vccz .LBB0_1324

.Lh8_a:
	v_cmp_gt_i64_e32 vcc, s[18:19], v[176:177]
	v_cmp_lt_i64_e64 s[40:41], s[18:19], v[174:175]
	s_cbranch_vccnz .LBB0_1313
	s_ashr_i32 s1, s18, 31
	s_lshr_b32 s1, s1, 29
	s_add_i32 s1, s18, s1
	s_ashr_i32 s19, s1, 3
	s_and_b32 s1, s1, -8
	s_sub_i32 s1, s18, s1
	s_cmp_lt_i32 s1, 0
	s_cselect_b32 s18, 41, 40
	s_mul_i32 s1, s18, s1
	s_add_i32 s1, s1, s19
	s_ashr_i32 s18, s1, 31
	s_lshr_b32 s18, s18, 28
	s_add_i32 s18, s1, s18
	s_ashr_i32 s19, s18, 4
	s_lshl_b32 s19, s19, 2
	s_sub_i32 s36, 0x50, s19
	s_min_i32 s37, s36, 4
	s_abs_i32 s36, s37
	v_cvt_f32_u32_e32 v0, s36
	s_sub_i32 s55, 0, s36
	s_and_b32 s18, s18, -16
	s_sub_i32 s1, s1, s18
	v_rcp_iflag_f32_e32 v0, v0
	s_abs_i32 s18, s1
	s_xor_b32 s54, s1, s37
	s_ashr_i32 s54, s54, 31
	v_mul_f32_e32 v0, 0x4f7ffffe, v0
	v_cvt_u32_f32_e32 v0, v0
	s_nop 0
	v_readfirstlane_b32 s56, v0
	s_mul_i32 s55, s55, s56
	s_mul_hi_u32 s55, s56, s55
	s_add_i32 s56, s56, s55
	s_mul_hi_u32 s55, s18, s56
	s_mul_i32 s56, s55, s36
	s_sub_i32 s18, s18, s56
	s_add_i32 s57, s55, 1
	s_sub_i32 s56, s18, s36
	s_cmp_ge_u32 s18, s36
	s_cselect_b32 s55, s57, s55
	s_cselect_b32 s18, s56, s18
	s_add_i32 s56, s55, 1
	s_cmp_ge_u32 s18, s36
	s_cselect_b32 s18, s56, s55
	s_xor_b32 s18, s18, s54
	s_sub_i32 s36, s18, s54
	s_mul_i32 s18, s36, s37
	s_sub_i32 s1, s1, s18
	s_add_i32 s54, s1, s19
.LBB0_1313:
	s_ashr_i32 s55, s54, 31
	s_lshl_b64 s[18:19], s[54:55], 19
	s_add_u32 s56, s17, s18
	s_addc_u32 s57, s21, s19
	s_cmp_lg_u32 s101, 2
	s_cbranch_scc1 .Lh8_b
	s_add_u32 s56, s56, 0x40000
	s_addc_u32 s57, s57, 0
.Lh8_b:
	s_ashr_i32 s37, s36, 31
	s_lshl_b64 s[18:19], s[36:37], 19
	s_add_u32 s60, s22, s18
	v_mov_b32_e32 v141, 0
	s_addc_u32 s61, s23, s19
	s_andn2_b64 vcc, exec, s[46:47]
	s_waitcnt lgkmcnt(0)
	s_cbranch_vccnz .LBB0_1317
	s_and_b64 s[18:19], s[40:41], exec
	s_cselect_b32 s1, s57, s27
	s_cselect_b32 s37, s56, s26
	s_cselect_b32 s55, s61, s3
	s_cselect_b32 s89, s60, s2
	s_add_u32 vcc_lo, s26, 0x100
	s_addc_u32 vcc_hi, s27, 0
	s_add_u32 s90, s2, 0x100
	s_addc_u32 s91, s3, 0
	s_add_u32 s94, s26, 0x40080
	v_mov_b32_e32 v2, 0
	s_addc_u32 s95, s27, 0
	s_mov_b32 s18, 0
	v_mov_b32_e32 v3, v2
	v_mov_b32_e32 v4, v2
	v_mov_b32_e32 v5, v2
	v_mov_b32_e32 v6, v2
	v_mov_b32_e32 v7, v2
	v_mov_b32_e32 v8, v2
	v_mov_b32_e32 v9, v2
	v_mov_b32_e32 v18, v2
	v_mov_b32_e32 v19, v2
	v_mov_b32_e32 v20, v2
	v_mov_b32_e32 v21, v2
	v_mov_b32_e32 v22, v2
	v_mov_b32_e32 v23, v2
	v_mov_b32_e32 v24, v2
	v_mov_b32_e32 v25, v2
	v_mov_b32_e32 v34, v2
	v_mov_b32_e32 v35, v2
	v_mov_b32_e32 v36, v2
	v_mov_b32_e32 v37, v2
	v_mov_b32_e32 v38, v2
	v_mov_b32_e32 v39, v2
	v_mov_b32_e32 v40, v2
	v_mov_b32_e32 v41, v2
	v_mov_b32_e32 v50, v2
	v_mov_b32_e32 v51, v2
	v_mov_b32_e32 v52, v2
	v_mov_b32_e32 v53, v2
	v_mov_b32_e32 v54, v2
	v_mov_b32_e32 v55, v2
	v_mov_b32_e32 v56, v2
	v_mov_b32_e32 v57, v2
	v_mov_b32_e32 v10, v2
	v_mov_b32_e32 v11, v2
	v_mov_b32_e32 v12, v2
	v_mov_b32_e32 v13, v2
	v_mov_b32_e32 v14, v2
	v_mov_b32_e32 v15, v2
	v_mov_b32_e32 v16, v2
	v_mov_b32_e32 v17, v2
	v_mov_b32_e32 v26, v2
	v_mov_b32_e32 v27, v2
	v_mov_b32_e32 v28, v2
	v_mov_b32_e32 v29, v2
	v_mov_b32_e32 v30, v2
	v_mov_b32_e32 v31, v2
	v_mov_b32_e32 v32, v2
	v_mov_b32_e32 v33, v2
	v_mov_b32_e32 v42, v2
	v_mov_b32_e32 v43, v2
	v_mov_b32_e32 v44, v2
	v_mov_b32_e32 v45, v2
	v_mov_b32_e32 v46, v2
	v_mov_b32_e32 v47, v2
	v_mov_b32_e32 v48, v2
	v_mov_b32_e32 v49, v2
	v_mov_b32_e32 v58, v2
	v_mov_b32_e32 v59, v2
	v_mov_b32_e32 v60, v2
	v_mov_b32_e32 v61, v2
	v_mov_b32_e32 v62, v2
	v_mov_b32_e32 v63, v2
	v_mov_b32_e32 v64, v2
	v_mov_b32_e32 v65, v2
	v_mov_b32_e32 v82, v2
	v_mov_b32_e32 v83, v2
	v_mov_b32_e32 v84, v2
	v_mov_b32_e32 v85, v2
	v_mov_b32_e32 v86, v2
	v_mov_b32_e32 v87, v2
	v_mov_b32_e32 v88, v2
	v_mov_b32_e32 v89, v2
	v_mov_b32_e32 v98, v2
	v_mov_b32_e32 v99, v2
	v_mov_b32_e32 v100, v2
	v_mov_b32_e32 v101, v2
	v_mov_b32_e32 v102, v2
	v_mov_b32_e32 v103, v2
	v_mov_b32_e32 v104, v2
	v_mov_b32_e32 v105, v2
	v_mov_b32_e32 v114, v2
	v_mov_b32_e32 v115, v2
	v_mov_b32_e32 v116, v2
	v_mov_b32_e32 v117, v2
	v_mov_b32_e32 v118, v2
	v_mov_b32_e32 v119, v2
	v_mov_b32_e32 v120, v2
	v_mov_b32_e32 v121, v2
	v_mov_b32_e32 v130, v2
	v_mov_b32_e32 v131, v2
	v_mov_b32_e32 v132, v2
	v_mov_b32_e32 v133, v2
	v_mov_b32_e32 v134, v2
	v_mov_b32_e32 v135, v2
	v_mov_b32_e32 v136, v2
	v_mov_b32_e32 v137, v2
	v_mov_b32_e32 v90, v2
	v_mov_b32_e32 v91, v2
	v_mov_b32_e32 v92, v2
	v_mov_b32_e32 v93, v2
	v_mov_b32_e32 v94, v2
	v_mov_b32_e32 v95, v2
	v_mov_b32_e32 v96, v2
	v_mov_b32_e32 v97, v2
	v_mov_b32_e32 v106, v2
	v_mov_b32_e32 v107, v2
	v_mov_b32_e32 v108, v2
	v_mov_b32_e32 v109, v2
	v_mov_b32_e32 v110, v2
	v_mov_b32_e32 v111, v2
	v_mov_b32_e32 v112, v2
	v_mov_b32_e32 v113, v2
	v_mov_b32_e32 v122, v2
	v_mov_b32_e32 v123, v2
	v_mov_b32_e32 v124, v2
	v_mov_b32_e32 v125, v2
	v_mov_b32_e32 v126, v2
	v_mov_b32_e32 v127, v2
	v_mov_b32_e32 v128, v2
	v_mov_b32_e32 v129, v2
	v_mov_b32_e32 v142, v2
	v_mov_b32_e32 v143, v2
	v_mov_b32_e32 v144, v2
	v_mov_b32_e32 v145, v2
	v_mov_b32_e32 v138, v2
	v_mov_b32_e32 v139, v2
	v_mov_b32_e32 v140, v2
	v_mov_b32_e32 v141, v2
.LBB0_1315:
	s_add_i32 s92, s18, 2
	s_cmp_eq_u32 s81, s18
	s_cselect_b32 s18, s37, vcc_lo
	s_cselect_b32 s19, s1, vcc_hi
	s_cselect_b32 s62, s89, s90
	s_cselect_b32 s63, s55, s91
	s_add_u32 s26, s18, 0x80
	s_addc_u32 s27, s19, 0
	s_add_i32 s93, 0, 0x10000
	v_add_u32_e32 v0, s93, v222
	s_add_i32 s96, 0, 0x14000
	ds_read_b128 v[66:69], v0
	ds_read_b128 v[70:73], v0 offset:1024
	ds_read_b128 v[74:77], v0 offset:2048
	ds_read_b128 v[78:81], v0 offset:3072
	v_add_u32_e32 v0, s96, v222
	ds_read_b128 v[146:149], v0
	ds_read_b128 v[150:153], v0 offset:1024
	ds_read_b128 v[154:157], v0 offset:2048
	ds_read_b128 v[158:161], v0 offset:3072
	s_mov_b64 s[2:3], s[94:95]
	ds_read_b128 v[162:165], v223
	ds_read_b128 v[166:169], v223 offset:1024
	ds_read_b128 v[198:201], v223 offset:2048
	ds_read_b128 v[202:205], v223 offset:3072
	ds_read_b128 v[206:209], v223 offset:4096
	ds_read_b128 v[210:213], v223 offset:5120
	ds_read_b128 v[214:217], v223 offset:6144
	ds_read_b128 v[218:221], v223 offset:7168
	s_add_i32 m0, s67, 0xc000
	v_lshl_add_u64 v[224:225], s[2:3], 0, v[196:197]
	global_load_lds_dwordx4 v[224:225], off
	v_lshl_add_u64 v[224:225], s[2:3], 0, v[172:173]
	s_add_i32 m0, s67, 0xe000
	s_nop 0
	global_load_lds_dwordx4 v[224:225], off
	s_waitcnt vmcnt(8)
	s_waitcnt lgkmcnt(0)
	s_barrier
	s_setprio 1
	s_waitcnt lgkmcnt(0)
	v_mfma_f32_16x16x32_bf16 v[138:141], v[66:69], v[162:165], v[138:141]
	v_mfma_f32_16x16x32_bf16 v[142:145], v[74:77], v[162:165], v[142:145]
	v_mfma_f32_16x16x32_bf16 v[126:129], v[66:69], v[198:201], v[126:129]
	v_mfma_f32_16x16x32_bf16 v[122:125], v[74:77], v[198:201], v[122:125]
	v_mfma_f32_16x16x32_bf16 v[110:113], v[66:69], v[206:209], v[110:113]
	v_mfma_f32_16x16x32_bf16 v[106:109], v[74:77], v[206:209], v[106:109]
	v_mfma_f32_16x16x32_bf16 v[94:97], v[66:69], v[214:217], v[94:97]
	v_mfma_f32_16x16x32_bf16 v[90:93], v[74:77], v[214:217], v[90:93]
	v_mfma_f32_16x16x32_bf16 v[138:141], v[70:73], v[166:169], v[138:141]
	v_mfma_f32_16x16x32_bf16 v[142:145], v[78:81], v[166:169], v[142:145]
	v_mfma_f32_16x16x32_bf16 v[126:129], v[70:73], v[202:205], v[126:129]
	v_mfma_f32_16x16x32_bf16 v[122:125], v[78:81], v[202:205], v[122:125]
	v_mfma_f32_16x16x32_bf16 v[110:113], v[70:73], v[210:213], v[110:113]
	v_mfma_f32_16x16x32_bf16 v[106:109], v[78:81], v[210:213], v[106:109]
	v_mfma_f32_16x16x32_bf16 v[94:97], v[70:73], v[218:221], v[94:97]
	v_mfma_f32_16x16x32_bf16 v[90:93], v[78:81], v[218:221], v[90:93]
	v_mfma_f32_16x16x32_bf16 v[134:137], v[146:149], v[162:165], v[134:137]
	v_mfma_f32_16x16x32_bf16 v[130:133], v[154:157], v[162:165], v[130:133]
	v_mfma_f32_16x16x32_bf16 v[118:121], v[146:149], v[198:201], v[118:121]
	v_mfma_f32_16x16x32_bf16 v[114:117], v[154:157], v[198:201], v[114:117]
	v_mfma_f32_16x16x32_bf16 v[102:105], v[146:149], v[206:209], v[102:105]
	v_mfma_f32_16x16x32_bf16 v[98:101], v[154:157], v[206:209], v[98:101]
	v_mfma_f32_16x16x32_bf16 v[86:89], v[146:149], v[214:217], v[86:89]
	v_mfma_f32_16x16x32_bf16 v[82:85], v[154:157], v[214:217], v[82:85]
	v_mfma_f32_16x16x32_bf16 v[134:137], v[150:153], v[166:169], v[134:137]
	v_mfma_f32_16x16x32_bf16 v[130:133], v[158:161], v[166:169], v[130:133]
	v_mfma_f32_16x16x32_bf16 v[118:121], v[150:153], v[202:205], v[118:121]
	v_mfma_f32_16x16x32_bf16 v[114:117], v[158:161], v[202:205], v[114:117]
	v_mfma_f32_16x16x32_bf16 v[102:105], v[150:153], v[210:213], v[102:105]
	v_mfma_f32_16x16x32_bf16 v[98:101], v[158:161], v[210:213], v[98:101]
	v_mfma_f32_16x16x32_bf16 v[86:89], v[150:153], v[218:221], v[86:89]
	v_mfma_f32_16x16x32_bf16 v[82:85], v[158:161], v[218:221], v[82:85]
	s_setprio 0
	s_barrier
	s_mov_b64 s[2:3], s[62:63]
	s_add_i32 s93, s93, s25
	ds_read_b128 v[162:165], v223 offset:16384
	ds_read_b128 v[166:169], v223 offset:17408
	ds_read_b128 v[198:201], v223 offset:18432
	ds_read_b128 v[202:205], v223 offset:19456
	ds_read_b128 v[206:209], v223 offset:20480
	ds_read_b128 v[210:213], v223 offset:21504
	ds_read_b128 v[214:217], v223 offset:22528
	ds_read_b128 v[218:221], v223 offset:23552
	s_mov_b32 m0, s93
	v_lshl_add_u64 v[224:225], s[2:3], 0, v[194:195]
	global_load_lds_dwordx4 v[224:225], off
	s_add_i32 m0, s93, 0x2000
	v_lshl_add_u64 v[224:225], s[2:3], 0, v[170:171]
	s_add_u32 s2, s62, 0x40000
	s_addc_u32 s3, s63, 0
	s_add_i32 s93, s96, s25
	global_load_lds_dwordx4 v[224:225], off
	s_mov_b32 m0, s93
	v_lshl_add_u64 v[224:225], s[2:3], 0, v[194:195]
	global_load_lds_dwordx4 v[224:225], off
	v_lshl_add_u64 v[224:225], s[2:3], 0, v[170:171]
	s_add_i32 m0, s93, 0x2000
	s_mov_b64 s[2:3], s[18:19]
	global_load_lds_dwordx4 v[224:225], off
	s_mov_b32 m0, s67
	v_lshl_add_u64 v[224:225], s[2:3], 0, v[196:197]
	global_load_lds_dwordx4 v[224:225], off
	v_lshl_add_u64 v[224:225], s[2:3], 0, v[172:173]
	s_mov_b32 m0, s68
	s_nop 0
	global_load_lds_dwordx4 v[224:225], off
	s_waitcnt vmcnt(8)
	s_waitcnt lgkmcnt(0)
	s_barrier
	s_setprio 1
	s_waitcnt lgkmcnt(0)
	s_cmp_lg_u32 s100, 0
	s_cbranch_scc1 .Lh8_m0
	v_mfma_f32_16x16x32_bf16 v[62:65], v[66:69], v[162:165], v[62:65]
	v_mfma_f32_16x16x32_bf16 v[58:61], v[74:77], v[162:165], v[58:61]
	v_mfma_f32_16x16x32_bf16 v[46:49], v[66:69], v[198:201], v[46:49]
	v_mfma_f32_16x16x32_bf16 v[42:45], v[74:77], v[198:201], v[42:45]
	v_mfma_f32_16x16x32_bf16 v[30:33], v[66:69], v[206:209], v[30:33]
	v_mfma_f32_16x16x32_bf16 v[26:29], v[74:77], v[206:209], v[26:29]
	v_mfma_f32_16x16x32_bf16 v[14:17], v[66:69], v[214:217], v[14:17]
	v_mfma_f32_16x16x32_bf16 v[10:13], v[74:77], v[214:217], v[10:13]
	v_mfma_f32_16x16x32_bf16 v[62:65], v[70:73], v[166:169], v[62:65]
	v_mfma_f32_16x16x32_bf16 v[58:61], v[78:81], v[166:169], v[58:61]
	v_mfma_f32_16x16x32_bf16 v[46:49], v[70:73], v[202:205], v[46:49]
	v_mfma_f32_16x16x32_bf16 v[42:45], v[78:81], v[202:205], v[42:45]
	v_mfma_f32_16x16x32_bf16 v[30:33], v[70:73], v[210:213], v[30:33]
	v_mfma_f32_16x16x32_bf16 v[26:29], v[78:81], v[210:213], v[26:29]
	v_mfma_f32_16x16x32_bf16 v[14:17], v[70:73], v[218:221], v[14:17]
	v_mfma_f32_16x16x32_bf16 v[10:13], v[78:81], v[218:221], v[10:13]
	v_mfma_f32_16x16x32_bf16 v[54:57], v[146:149], v[162:165], v[54:57]
	v_mfma_f32_16x16x32_bf16 v[50:53], v[154:157], v[162:165], v[50:53]
	v_mfma_f32_16x16x32_bf16 v[38:41], v[146:149], v[198:201], v[38:41]
	v_mfma_f32_16x16x32_bf16 v[34:37], v[154:157], v[198:201], v[34:37]
	v_mfma_f32_16x16x32_bf16 v[22:25], v[146:149], v[206:209], v[22:25]
	v_mfma_f32_16x16x32_bf16 v[18:21], v[154:157], v[206:209], v[18:21]
	v_mfma_f32_16x16x32_bf16 v[6:9], v[146:149], v[214:217], v[6:9]
	v_mfma_f32_16x16x32_bf16 v[2:5], v[154:157], v[214:217], v[2:5]
	v_mfma_f32_16x16x32_bf16 v[54:57], v[150:153], v[166:169], v[54:57]
	v_mfma_f32_16x16x32_bf16 v[50:53], v[158:161], v[166:169], v[50:53]
	v_mfma_f32_16x16x32_bf16 v[38:41], v[150:153], v[202:205], v[38:41]
	v_mfma_f32_16x16x32_bf16 v[34:37], v[158:161], v[202:205], v[34:37]
	v_mfma_f32_16x16x32_bf16 v[22:25], v[150:153], v[210:213], v[22:25]
	v_mfma_f32_16x16x32_bf16 v[18:21], v[158:161], v[210:213], v[18:21]
	v_mfma_f32_16x16x32_bf16 v[6:9], v[150:153], v[218:221], v[6:9]
	v_mfma_f32_16x16x32_bf16 v[2:5], v[158:161], v[218:221], v[2:5]
.Lh8_m0:
	s_setprio 0
	s_barrier
	s_add_i32 s93, 0, 0x18000
	v_add_u32_e32 v0, s93, v222
	s_add_i32 s96, 0, 0x1c000
	ds_read_b128 v[66:69], v0
	ds_read_b128 v[70:73], v0 offset:1024
	ds_read_b128 v[74:77], v0 offset:2048
	ds_read_b128 v[78:81], v0 offset:3072
	v_add_u32_e32 v0, s96, v222
	ds_read_b128 v[146:149], v0
	ds_read_b128 v[150:153], v0 offset:1024
	ds_read_b128 v[154:157], v0 offset:2048
	ds_read_b128 v[158:161], v0 offset:3072
	s_add_u32 s2, s18, 0x40000
	s_addc_u32 s3, s19, 0
	s_mov_b32 m0, s69
	ds_read_b128 v[162:165], v223 offset:32768
	ds_read_b128 v[166:169], v223 offset:33792
	ds_read_b128 v[198:201], v223 offset:34816
	ds_read_b128 v[202:205], v223 offset:35840
	ds_read_b128 v[206:209], v223 offset:36864
	ds_read_b128 v[210:213], v223 offset:37888
	ds_read_b128 v[214:217], v223 offset:38912
	ds_read_b128 v[218:221], v223 offset:39936
	s_nop 0
	v_lshl_add_u64 v[224:225], s[2:3], 0, v[196:197]
	global_load_lds_dwordx4 v[224:225], off
	v_lshl_add_u64 v[224:225], s[2:3], 0, v[172:173]
	s_mov_b32 m0, s70
	s_nop 0
	global_load_lds_dwordx4 v[224:225], off
	s_waitcnt vmcnt(8)
	s_waitcnt lgkmcnt(0)
	s_barrier
	s_setprio 1
	s_waitcnt lgkmcnt(0)
	v_mfma_f32_16x16x32_bf16 v[138:141], v[66:69], v[162:165], v[138:141]
	v_mfma_f32_16x16x32_bf16 v[142:145], v[74:77], v[162:165], v[142:145]
	v_mfma_f32_16x16x32_bf16 v[126:129], v[66:69], v[198:201], v[126:129]
	v_mfma_f32_16x16x32_bf16 v[122:125], v[74:77], v[198:201], v[122:125]
	v_mfma_f32_16x16x32_bf16 v[110:113], v[66:69], v[206:209], v[110:113]
	v_mfma_f32_16x16x32_bf16 v[106:109], v[74:77], v[206:209], v[106:109]
	v_mfma_f32_16x16x32_bf16 v[94:97], v[66:69], v[214:217], v[94:97]
	v_mfma_f32_16x16x32_bf16 v[90:93], v[74:77], v[214:217], v[90:93]
	v_mfma_f32_16x16x32_bf16 v[138:141], v[70:73], v[166:169], v[138:141]
	v_mfma_f32_16x16x32_bf16 v[142:145], v[78:81], v[166:169], v[142:145]
	v_mfma_f32_16x16x32_bf16 v[126:129], v[70:73], v[202:205], v[126:129]
	v_mfma_f32_16x16x32_bf16 v[122:125], v[78:81], v[202:205], v[122:125]
	v_mfma_f32_16x16x32_bf16 v[110:113], v[70:73], v[210:213], v[110:113]
	v_mfma_f32_16x16x32_bf16 v[106:109], v[78:81], v[210:213], v[106:109]
	v_mfma_f32_16x16x32_bf16 v[94:97], v[70:73], v[218:221], v[94:97]
	v_mfma_f32_16x16x32_bf16 v[90:93], v[78:81], v[218:221], v[90:93]
	v_mfma_f32_16x16x32_bf16 v[134:137], v[146:149], v[162:165], v[134:137]
	v_mfma_f32_16x16x32_bf16 v[130:133], v[154:157], v[162:165], v[130:133]
	v_mfma_f32_16x16x32_bf16 v[118:121], v[146:149], v[198:201], v[118:121]
	v_mfma_f32_16x16x32_bf16 v[114:117], v[154:157], v[198:201], v[114:117]
	v_mfma_f32_16x16x32_bf16 v[102:105], v[146:149], v[206:209], v[102:105]
	v_mfma_f32_16x16x32_bf16 v[98:101], v[154:157], v[206:209], v[98:101]
	v_mfma_f32_16x16x32_bf16 v[86:89], v[146:149], v[214:217], v[86:89]
	v_mfma_f32_16x16x32_bf16 v[82:85], v[154:157], v[214:217], v[82:85]
	v_mfma_f32_16x16x32_bf16 v[134:137], v[150:153], v[166:169], v[134:137]
	v_mfma_f32_16x16x32_bf16 v[130:133], v[158:161], v[166:169], v[130:133]
	v_mfma_f32_16x16x32_bf16 v[118:121], v[150:153], v[202:205], v[118:121]
	v_mfma_f32_16x16x32_bf16 v[114:117], v[158:161], v[202:205], v[114:117]
	v_mfma_f32_16x16x32_bf16 v[102:105], v[150:153], v[210:213], v[102:105]
	v_mfma_f32_16x16x32_bf16 v[98:101], v[158:161], v[210:213], v[98:101]
	v_mfma_f32_16x16x32_bf16 v[86:89], v[150:153], v[218:221], v[86:89]
	v_mfma_f32_16x16x32_bf16 v[82:85], v[158:161], v[218:221], v[82:85]
	s_setprio 0
	s_barrier
	s_add_u32 s2, s62, 0x80
	s_addc_u32 s3, s63, 0
	s_add_i32 s18, s93, s25
	ds_read_b128 v[162:165], v223 offset:49152
	ds_read_b128 v[166:169], v223 offset:50176
	ds_read_b128 v[198:201], v223 offset:51200
	ds_read_b128 v[202:205], v223 offset:52224
	ds_read_b128 v[206:209], v223 offset:53248
	ds_read_b128 v[210:213], v223 offset:54272
	ds_read_b128 v[214:217], v223 offset:55296
	ds_read_b128 v[218:221], v223 offset:56320
	s_mov_b32 m0, s18
	v_lshl_add_u64 v[224:225], s[2:3], 0, v[194:195]
	global_load_lds_dwordx4 v[224:225], off
	s_add_i32 m0, s18, 0x2000
	v_lshl_add_u64 v[224:225], s[2:3], 0, v[170:171]
	s_add_u32 s2, s62, 0x40080
	s_addc_u32 s3, s63, 0
	s_add_i32 s18, s96, s25
	global_load_lds_dwordx4 v[224:225], off
	s_mov_b32 m0, s18
	v_lshl_add_u64 v[224:225], s[2:3], 0, v[194:195]
	global_load_lds_dwordx4 v[224:225], off
	v_lshl_add_u64 v[224:225], s[2:3], 0, v[170:171]
	s_add_i32 m0, s18, 0x2000
	s_nop 0
	global_load_lds_dwordx4 v[224:225], off
	s_mov_b32 m0, s82
	v_lshl_add_u64 v[224:225], s[26:27], 0, v[196:197]
	global_load_lds_dwordx4 v[224:225], off
	v_lshl_add_u64 v[224:225], s[26:27], 0, v[172:173]
	s_mov_b32 m0, s83
	s_nop 0
	global_load_lds_dwordx4 v[224:225], off
	s_waitcnt vmcnt(8)
	s_waitcnt lgkmcnt(0)
	s_barrier
	s_setprio 1
	s_waitcnt lgkmcnt(0)
	s_cmp_lg_u32 s100, 0
	s_cbranch_scc1 .Lh8_m1
	v_mfma_f32_16x16x32_bf16 v[62:65], v[66:69], v[162:165], v[62:65]
	v_mfma_f32_16x16x32_bf16 v[58:61], v[74:77], v[162:165], v[58:61]
	v_mfma_f32_16x16x32_bf16 v[46:49], v[66:69], v[198:201], v[46:49]
	v_mfma_f32_16x16x32_bf16 v[42:45], v[74:77], v[198:201], v[42:45]
	v_mfma_f32_16x16x32_bf16 v[30:33], v[66:69], v[206:209], v[30:33]
	v_mfma_f32_16x16x32_bf16 v[26:29], v[74:77], v[206:209], v[26:29]
	v_mfma_f32_16x16x32_bf16 v[14:17], v[66:69], v[214:217], v[14:17]
	v_mfma_f32_16x16x32_bf16 v[10:13], v[74:77], v[214:217], v[10:13]
	v_mfma_f32_16x16x32_bf16 v[62:65], v[70:73], v[166:169], v[62:65]
	v_mfma_f32_16x16x32_bf16 v[58:61], v[78:81], v[166:169], v[58:61]
	v_mfma_f32_16x16x32_bf16 v[46:49], v[70:73], v[202:205], v[46:49]
	v_mfma_f32_16x16x32_bf16 v[42:45], v[78:81], v[202:205], v[42:45]
	v_mfma_f32_16x16x32_bf16 v[30:33], v[70:73], v[210:213], v[30:33]
	v_mfma_f32_16x16x32_bf16 v[26:29], v[78:81], v[210:213], v[26:29]
	v_mfma_f32_16x16x32_bf16 v[14:17], v[70:73], v[218:221], v[14:17]
	v_mfma_f32_16x16x32_bf16 v[10:13], v[78:81], v[218:221], v[10:13]
	v_mfma_f32_16x16x32_bf16 v[54:57], v[146:149], v[162:165], v[54:57]
	v_mfma_f32_16x16x32_bf16 v[50:53], v[154:157], v[162:165], v[50:53]
	v_mfma_f32_16x16x32_bf16 v[38:41], v[146:149], v[198:201], v[38:41]
	v_mfma_f32_16x16x32_bf16 v[34:37], v[154:157], v[198:201], v[34:37]
	v_mfma_f32_16x16x32_bf16 v[22:25], v[146:149], v[206:209], v[22:25]
	v_mfma_f32_16x16x32_bf16 v[18:21], v[154:157], v[206:209], v[18:21]
	v_mfma_f32_16x16x32_bf16 v[6:9], v[146:149], v[214:217], v[6:9]
	v_mfma_f32_16x16x32_bf16 v[2:5], v[154:157], v[214:217], v[2:5]
	v_mfma_f32_16x16x32_bf16 v[54:57], v[150:153], v[166:169], v[54:57]
	v_mfma_f32_16x16x32_bf16 v[50:53], v[158:161], v[166:169], v[50:53]
	v_mfma_f32_16x16x32_bf16 v[38:41], v[150:153], v[202:205], v[38:41]
	v_mfma_f32_16x16x32_bf16 v[34:37], v[158:161], v[202:205], v[34:37]
	v_mfma_f32_16x16x32_bf16 v[22:25], v[150:153], v[210:213], v[22:25]
	v_mfma_f32_16x16x32_bf16 v[18:21], v[158:161], v[210:213], v[18:21]
	v_mfma_f32_16x16x32_bf16 v[6:9], v[150:153], v[218:221], v[6:9]
	v_mfma_f32_16x16x32_bf16 v[2:5], v[158:161], v[218:221], v[2:5]
.Lh8_m1:
	s_setprio 0
	s_barrier
	s_add_u32 vcc_lo, vcc_lo, 0x100
	s_addc_u32 vcc_hi, vcc_hi, 0
	s_add_u32 s90, s90, 0x100
	s_addc_u32 s91, s91, 0
	s_add_u32 s94, s94, 0x100
	s_addc_u32 s95, s95, 0
	s_cmp_ge_i32 s92, s84
	s_mov_b32 s18, s92
	s_cbranch_scc0 .LBB0_1315
	s_movk_i32 s90, 0x80
	s_mov_b32 s91, 0x10000
	s_mov_b32 s92, 0x12000
	s_mov_b32 s93, 0x14000
	s_mov_b32 s94, 0x16000
	s_movk_i32 s95, 0x4000
	s_movk_i32 s96, 0x3000
	s_mov_b32 s63, 0xa000

.LBB0_1319:
	v_mov_b32_e32 v66, v179
	s_cmp_eq_u32 s100, 2
	s_cselect_b32 vcc_lo, 0x80, 0
	s_lshl_b32 s1, s88, 8
	v_bfe_u32 v0, v66, 6, 2
	v_and_b32_e32 v225, 15, v66
	v_bfe_u32 v224, v66, 4, 2
	v_ashrrev_i32_e32 v66, 2, v66
	v_and_b32_e32 v66, 0xffffffc0, v66
	v_lshl_add_u32 v164, s0, 8, v66
	v_add_u32_e32 v164, vcc_lo, v164
	v_lshlrev_b32_e32 v66, 5, v0
	v_lshlrev_b32_e32 v67, 3, v224
	v_or3_b32 v216, v66, s1, v67
	s_add_i32 s1, s0, -16
	s_lshr_b32 s1, s1, 3
	s_add_i32 s1, s1, 1
	s_cmp_lt_i32 s0, 16
	s_cselect_b32 s0, 0, s1
	s_mul_i32 s19, s0, 0x6000
	s_mul_hi_u32 s18, s0, 0x6000
	s_cselect_b32 s1, s43, s86
	s_cselect_b32 s0, s42, s85
	s_add_u32 s2, s73, s19
	v_ashrrev_i32_e32 v217, 31, v216
	s_addc_u32 s3, s78, s18
	v_lshlrev_b64 v[162:163], 2, v[216:217]
	v_lshl_add_u64 v[154:155], s[2:3], 0, v[162:163]
	s_add_u32 s2, s79, s19
	s_addc_u32 s3, s80, s18
	v_lshl_add_u64 v[156:157], s[30:31], 0, v[162:163]
	v_lshl_add_u64 v[158:159], s[2:3], 0, v[162:163]
	global_load_dwordx4 v[74:77], v[154:155], off offset:16
	global_load_dwordx4 v[78:81], v[154:155], off
	global_load_dwordx4 v[66:69], v[156:157], off offset:16
	global_load_dwordx4 v[70:73], v[156:157], off
	global_load_dwordx4 v[146:149], v[158:159], off offset:16
	global_load_dwordx4 v[150:153], v[158:159], off
	v_or_b32_e32 v198, v164, v225
	v_ashrrev_i32_e32 v199, 31, v198
	v_lshl_add_u64 v[220:221], s[0:1], 0, v[162:163]
	v_or_b32_e32 v218, 16, v198
	v_ashrrev_i32_e32 v219, 31, v218
	v_lshlrev_b64 v[248:249], 10, v[198:199]
	v_lshl_add_u64 v[248:249], v[248:249], 0, v[216:217]
	v_cmp_eq_u32_e32 vcc, 0, v224
	s_waitcnt vmcnt(0)
	v_pk_add_f32 v[152:153], v[152:153], 1.0 op_sel_hi:[1,0]
	v_pk_add_f32 v[150:151], v[150:151], 1.0 op_sel_hi:[1,0]
	v_pk_mul_f32 v[208:209], v[72:73], v[152:153]
	v_pk_mul_f32 v[210:211], v[70:71], v[150:151]
	v_pk_add_f32 v[70:71], v[148:149], 1.0 op_sel_hi:[1,0]
	v_pk_add_f32 v[72:73], v[146:147], 1.0 op_sel_hi:[1,0]
	v_pk_mul_f32 v[212:213], v[68:69], v[70:71]
	v_pk_mul_f32 v[214:215], v[66:67], v[72:73]
	global_load_dwordx4 v[66:69], v[154:155], off offset:528
	global_load_dwordx4 v[70:73], v[154:155], off offset:512
	global_load_dwordx4 v[146:149], v[156:157], off offset:528
	global_load_dwordx4 v[150:153], v[156:157], off offset:512
	s_nop 0
	global_load_dwordx4 v[154:157], v[158:159], off offset:528
	s_nop 0
	global_load_dwordx4 v[158:161], v[158:159], off offset:512
	s_waitcnt vmcnt(0)
	v_pk_add_f32 v[160:161], v[160:161], 1.0 op_sel_hi:[1,0]
	s_nop 0
	v_pk_mul_f32 v[200:201], v[152:153], v[160:161]
	v_pk_add_f32 v[152:153], v[154:155], 1.0 op_sel_hi:[1,0]
	v_pk_add_f32 v[158:159], v[158:159], 1.0 op_sel_hi:[1,0]
	v_pk_mul_f32 v[206:207], v[146:147], v[152:153]
	v_lshlrev_b64 v[146:147], 12, v[198:199]
	v_lshl_add_u64 v[146:147], v[220:221], 0, v[146:147]
	global_load_dwordx4 v[226:229], v[146:147], off offset:16
	global_load_dwordx4 v[244:247], v[146:147], off
	global_load_dwordx4 v[162:165], v[146:147], off offset:528
	global_load_dwordx4 v[166:169], v[146:147], off offset:512
	v_pk_mul_f32 v[202:203], v[150:151], v[158:159]
	v_pk_add_f32 v[150:151], v[156:157], 1.0 op_sel_hi:[1,0]
	v_lshlrev_b64 v[146:147], 12, v[218:219]
	v_pk_mul_f32 v[204:205], v[148:149], v[150:151]
	v_lshl_add_u64 v[150:151], v[220:221], 0, v[146:147]
	global_load_dwordx4 v[154:157], v[150:151], off offset:16
	global_load_dwordx4 v[158:161], v[150:151], off
	global_load_dwordx4 v[146:149], v[150:151], off offset:528
	s_nop 0
	global_load_dwordx4 v[150:153], v[150:151], off offset:512
	s_waitcnt vmcnt(0)
	v_pk_fma_f32 v[144:145], v[144:145], v[76:77], v[228:229]
	v_pk_fma_f32 v[246:247], v[140:141], v[80:81], v[246:247]
	v_pk_fma_f32 v[244:245], v[138:139], v[78:79], v[244:245]
	v_mul_f32_e32 v141, v247, v247
	v_mul_f32_e32 v140, v245, v245
	v_pk_fma_f32 v[142:143], v[142:143], v[74:75], v[226:227]
	v_fmac_f32_e32 v140, v244, v244
	v_fmac_f32_e32 v141, v246, v246
	v_add_f32_e32 v140, v140, v141
	v_mul_f32_e32 v141, v143, v143
	v_mul_f32_e32 v226, v145, v145
	v_fmac_f32_e32 v141, v142, v142
	v_fmac_f32_e32 v226, v144, v144
	v_lshl_add_u64 v[138:139], v[248:249], 2, s[44:45]
	v_add_f32_e32 v141, v141, v226
	global_store_dwordx4 v[138:139], v[244:247], off
	global_store_dwordx4 v[138:139], v[142:145], off offset:16
	v_add_f32_e32 v228, v140, v141
	v_pk_mul_f32 v[140:141], v[210:211], v[244:245]
	v_pk_mul_f32 v[144:145], v[212:213], v[144:145]
	v_pk_mul_f32 v[142:143], v[214:215], v[142:143]
	v_pk_mul_f32 v[226:227], v[208:209], v[246:247]
	v_cvt_pk_bf16_f32 v140, v140, v141
	v_pk_fma_f32 v[136:137], v[136:137], v[72:73], v[168:169]
	v_cvt_pk_bf16_f32 v141, v226, v227
	v_cvt_pk_bf16_f32 v142, v142, v143
	v_cvt_pk_bf16_f32 v143, v144, v145
	v_lshl_add_u64 v[144:145], v[248:249], 1, s[34:35]
	v_pk_fma_f32 v[134:135], v[134:135], v[70:71], v[166:167]
	global_store_dwordx4 v[144:145], v[140:143], off
	v_pk_fma_f32 v[132:133], v[132:133], v[68:69], v[164:165]
	v_pk_fma_f32 v[130:131], v[130:131], v[66:67], v[162:163]
	global_store_dwordx4 v[138:139], v[134:137], off offset:512
	global_store_dwordx4 v[138:139], v[130:133], off offset:528
	v_mul_f32_e32 v138, v135, v135
	v_mul_f32_e32 v139, v137, v137
	v_fmac_f32_e32 v138, v134, v134
	v_fmac_f32_e32 v139, v136, v136
	v_add_f32_e32 v138, v138, v139
	v_mul_f32_e32 v139, v131, v131
	v_mul_f32_e32 v140, v133, v133
	v_fmac_f32_e32 v139, v130, v130
	v_fmac_f32_e32 v140, v132, v132
	v_add_f32_e32 v139, v139, v140
	v_add_f32_e32 v138, v138, v139
	v_pk_mul_f32 v[134:135], v[202:203], v[134:135]
	v_pk_fma_f32 v[128:129], v[128:129], v[80:81], v[160:161]
	v_pk_fma_f32 v[126:127], v[126:127], v[78:79], v[158:159]
	v_add_f32_e32 v142, v228, v138
	v_pk_mul_f32 v[136:137], v[200:201], v[136:137]
	v_pk_mul_f32 v[138:139], v[204:205], v[132:133]
	v_pk_mul_f32 v[132:133], v[206:207], v[130:131]
	v_cvt_pk_bf16_f32 v130, v134, v135
	v_cvt_pk_bf16_f32 v131, v136, v137
	v_mul_f32_e32 v134, v127, v127
	v_mul_f32_e32 v135, v129, v129
	v_cvt_pk_bf16_f32 v132, v132, v133
	v_cvt_pk_bf16_f32 v133, v138, v139
	global_store_dwordx4 v[144:145], v[130:133], off offset:256
	v_pk_fma_f32 v[124:125], v[124:125], v[76:77], v[156:157]
	v_pk_fma_f32 v[122:123], v[122:123], v[74:75], v[154:155]
	v_lshlrev_b64 v[130:131], 10, v[218:219]
	v_fmac_f32_e32 v134, v126, v126
	v_fmac_f32_e32 v135, v128, v128
	v_lshl_add_u64 v[130:131], v[130:131], 0, v[216:217]
	v_add_f32_e32 v134, v134, v135
	v_mul_f32_e32 v135, v123, v123
	v_mul_f32_e32 v136, v125, v125
	v_lshl_add_u64 v[132:133], v[130:131], 2, s[44:45]
	v_fmac_f32_e32 v135, v122, v122
	v_fmac_f32_e32 v136, v124, v124
	global_store_dwordx4 v[132:133], v[126:129], off
	global_store_dwordx4 v[132:133], v[122:125], off offset:16
	v_add_f32_e32 v135, v135, v136
	v_pk_mul_f32 v[126:127], v[210:211], v[126:127]
	v_add_f32_e32 v136, v134, v135
	v_pk_mul_f32 v[128:129], v[208:209], v[128:129]
	v_pk_mul_f32 v[134:135], v[212:213], v[124:125]
	v_pk_mul_f32 v[124:125], v[214:215], v[122:123]
	v_cvt_pk_bf16_f32 v122, v126, v127
	v_cvt_pk_bf16_f32 v123, v128, v129
	v_lshl_add_u64 v[126:127], v[130:131], 1, s[34:35]
	v_pk_fma_f32 v[120:121], v[120:121], v[72:73], v[152:153]
	v_pk_fma_f32 v[118:119], v[118:119], v[70:71], v[150:151]
	v_cvt_pk_bf16_f32 v124, v124, v125
	v_cvt_pk_bf16_f32 v125, v134, v135
	global_store_dwordx4 v[126:127], v[122:125], off
	v_pk_fma_f32 v[116:117], v[116:117], v[68:69], v[148:149]
	v_pk_fma_f32 v[114:115], v[114:115], v[66:67], v[146:147]
	v_mul_f32_e32 v122, v119, v119
	v_mul_f32_e32 v123, v121, v121
	v_fmac_f32_e32 v122, v118, v118
	v_fmac_f32_e32 v123, v120, v120
	v_add_f32_e32 v122, v122, v123
	v_mul_f32_e32 v123, v115, v115
	v_mul_f32_e32 v124, v117, v117
	v_fmac_f32_e32 v123, v114, v114
	v_fmac_f32_e32 v124, v116, v116
	v_add_f32_e32 v123, v123, v124
	v_add_f32_e32 v122, v122, v123
	v_or_b32_e32 v138, 32, v198
	global_store_dwordx4 v[132:133], v[118:121], off offset:512
	global_store_dwordx4 v[132:133], v[114:117], off offset:528
	v_add_f32_e32 v143, v136, v122
	v_pk_mul_f32 v[120:121], v[200:201], v[120:121]
	v_pk_mul_f32 v[118:119], v[202:203], v[118:119]
	v_pk_mul_f32 v[122:123], v[204:205], v[116:117]
	v_pk_mul_f32 v[116:117], v[206:207], v[114:115]
	v_cvt_pk_bf16_f32 v114, v118, v119
	v_cvt_pk_bf16_f32 v115, v120, v121
	v_ashrrev_i32_e32 v139, 31, v138
	v_cvt_pk_bf16_f32 v116, v116, v117
	v_cvt_pk_bf16_f32 v117, v122, v123
	global_store_dwordx4 v[126:127], v[114:117], off offset:256
	v_or_b32_e32 v140, 48, v198
	v_ashrrev_i32_e32 v141, 31, v140
	v_lshlrev_b64 v[114:115], 12, v[138:139]
	v_lshl_add_u64 v[114:115], v[220:221], 0, v[114:115]
	global_load_dwordx4 v[144:147], v[114:115], off offset:16
	global_load_dwordx4 v[148:151], v[114:115], off
	global_load_dwordx4 v[130:133], v[114:115], off offset:528
	global_load_dwordx4 v[134:137], v[114:115], off offset:512
	v_lshlrev_b64 v[114:115], 12, v[140:141]
	v_lshl_add_u64 v[118:119], v[220:221], 0, v[114:115]
	global_load_dwordx4 v[122:125], v[118:119], off offset:16
	global_load_dwordx4 v[126:129], v[118:119], off
	global_load_dwordx4 v[114:117], v[118:119], off offset:528
	s_nop 0
	global_load_dwordx4 v[118:121], v[118:119], off offset:512
	v_lshlrev_b64 v[152:153], 10, v[138:139]
	v_lshl_add_u64 v[152:153], v[152:153], 0, v[216:217]
	s_waitcnt vmcnt(0)
	v_pk_fma_f32 v[108:109], v[108:109], v[76:77], v[146:147]
	v_pk_fma_f32 v[112:113], v[112:113], v[80:81], v[150:151]
	v_pk_fma_f32 v[110:111], v[110:111], v[78:79], v[148:149]
	v_mul_f32_e32 v147, v113, v113
	v_mul_f32_e32 v146, v111, v111
	v_pk_fma_f32 v[106:107], v[106:107], v[74:75], v[144:145]
	v_fmac_f32_e32 v146, v110, v110
	v_fmac_f32_e32 v147, v112, v112
	v_add_f32_e32 v146, v146, v147
	v_mul_f32_e32 v147, v107, v107
	v_mul_f32_e32 v148, v109, v109
	v_lshl_add_u64 v[144:145], v[152:153], 2, s[44:45]
	v_fmac_f32_e32 v147, v106, v106
	v_fmac_f32_e32 v148, v108, v108
	global_store_dwordx4 v[144:145], v[110:113], off
	global_store_dwordx4 v[144:145], v[106:109], off offset:16
	v_add_f32_e32 v147, v147, v148
	v_pk_mul_f32 v[110:111], v[210:211], v[110:111]
	v_add_f32_e32 v148, v146, v147
	v_pk_mul_f32 v[112:113], v[208:209], v[112:113]
	v_pk_mul_f32 v[146:147], v[212:213], v[108:109]
	v_pk_mul_f32 v[108:109], v[214:215], v[106:107]
	v_cvt_pk_bf16_f32 v106, v110, v111
	v_cvt_pk_bf16_f32 v107, v112, v113
	v_lshl_add_u64 v[110:111], v[152:153], 1, s[34:35]
	v_pk_fma_f32 v[104:105], v[104:105], v[72:73], v[136:137]
	v_pk_fma_f32 v[102:103], v[102:103], v[70:71], v[134:135]
	v_cvt_pk_bf16_f32 v108, v108, v109
	v_cvt_pk_bf16_f32 v109, v146, v147
	global_store_dwordx4 v[110:111], v[106:109], off
	v_pk_fma_f32 v[100:101], v[100:101], v[68:69], v[132:133]
	v_pk_fma_f32 v[98:99], v[98:99], v[66:67], v[130:131]
	v_mul_f32_e32 v106, v103, v103
	v_mul_f32_e32 v107, v105, v105
	v_fmac_f32_e32 v106, v102, v102
	v_fmac_f32_e32 v107, v104, v104
	v_add_f32_e32 v106, v106, v107
	v_mul_f32_e32 v107, v99, v99
	v_mul_f32_e32 v108, v101, v101
	v_fmac_f32_e32 v107, v98, v98
	v_fmac_f32_e32 v108, v100, v100
	v_add_f32_e32 v107, v107, v108
	global_store_dwordx4 v[144:145], v[102:105], off offset:512
	global_store_dwordx4 v[144:145], v[98:101], off offset:528
	v_add_f32_e32 v106, v106, v107
	v_pk_mul_f32 v[102:103], v[202:203], v[102:103]
	v_pk_fma_f32 v[96:97], v[96:97], v[80:81], v[128:129]
	v_pk_fma_f32 v[94:95], v[94:95], v[78:79], v[126:127]
	v_add_f32_e32 v130, v148, v106
	v_pk_mul_f32 v[104:105], v[200:201], v[104:105]
	v_pk_mul_f32 v[106:107], v[204:205], v[100:101]
	v_pk_mul_f32 v[100:101], v[206:207], v[98:99]
	v_cvt_pk_bf16_f32 v98, v102, v103
	v_cvt_pk_bf16_f32 v99, v104, v105
	v_mul_f32_e32 v102, v95, v95
	v_mul_f32_e32 v103, v97, v97
	v_cvt_pk_bf16_f32 v100, v100, v101
	v_cvt_pk_bf16_f32 v101, v106, v107
	global_store_dwordx4 v[110:111], v[98:101], off offset:256
	v_pk_fma_f32 v[92:93], v[92:93], v[76:77], v[124:125]
	v_pk_fma_f32 v[90:91], v[90:91], v[74:75], v[122:123]
	v_lshlrev_b64 v[98:99], 10, v[140:141]
	v_fmac_f32_e32 v102, v94, v94
	v_fmac_f32_e32 v103, v96, v96
	v_lshl_add_u64 v[98:99], v[98:99], 0, v[216:217]
	v_add_f32_e32 v102, v102, v103
	v_mul_f32_e32 v103, v91, v91
	v_mul_f32_e32 v104, v93, v93
	v_lshl_add_u64 v[100:101], v[98:99], 2, s[44:45]
	v_fmac_f32_e32 v103, v90, v90
	v_fmac_f32_e32 v104, v92, v92
	global_store_dwordx4 v[100:101], v[94:97], off
	global_store_dwordx4 v[100:101], v[90:93], off offset:16
	v_add_f32_e32 v103, v103, v104
	v_pk_mul_f32 v[94:95], v[210:211], v[94:95]
	v_add_f32_e32 v104, v102, v103
	v_pk_mul_f32 v[96:97], v[208:209], v[96:97]
	v_pk_mul_f32 v[102:103], v[212:213], v[92:93]
	v_pk_mul_f32 v[92:93], v[214:215], v[90:91]
	v_cvt_pk_bf16_f32 v90, v94, v95
	v_cvt_pk_bf16_f32 v91, v96, v97
	v_lshl_add_u64 v[94:95], v[98:99], 1, s[34:35]
	v_pk_fma_f32 v[88:89], v[88:89], v[72:73], v[120:121]
	v_pk_fma_f32 v[86:87], v[86:87], v[70:71], v[118:119]
	v_cvt_pk_bf16_f32 v92, v92, v93
	v_cvt_pk_bf16_f32 v93, v102, v103
	global_store_dwordx4 v[94:95], v[90:93], off
	v_pk_fma_f32 v[84:85], v[84:85], v[68:69], v[116:117]
	v_pk_fma_f32 v[82:83], v[82:83], v[66:67], v[114:115]
	v_mul_f32_e32 v90, v87, v87
	v_mul_f32_e32 v91, v89, v89
	v_fmac_f32_e32 v90, v86, v86
	v_fmac_f32_e32 v91, v88, v88
	v_add_f32_e32 v90, v90, v91
	v_mul_f32_e32 v91, v83, v83
	v_mul_f32_e32 v92, v85, v85
	v_fmac_f32_e32 v91, v82, v82
	v_fmac_f32_e32 v92, v84, v84
	v_add_f32_e32 v91, v91, v92
	v_add_f32_e32 v90, v90, v91
	v_add_u32_e32 v114, 0x80, v198
	global_store_dwordx4 v[100:101], v[86:89], off offset:512
	global_store_dwordx4 v[100:101], v[82:85], off offset:528
	v_add_f32_e32 v118, v104, v90
	v_pk_mul_f32 v[88:89], v[200:201], v[88:89]
	v_pk_mul_f32 v[86:87], v[202:203], v[86:87]
	v_pk_mul_f32 v[90:91], v[204:205], v[84:85]
	v_pk_mul_f32 v[84:85], v[206:207], v[82:83]
	v_cvt_pk_bf16_f32 v82, v86, v87
	v_cvt_pk_bf16_f32 v83, v88, v89
	v_ashrrev_i32_e32 v115, 31, v114
	v_cvt_pk_bf16_f32 v84, v84, v85
	v_cvt_pk_bf16_f32 v85, v90, v91
	global_store_dwordx4 v[94:95], v[82:85], off offset:256
	s_cmp_lg_u32 s100, 0
	s_cbranch_scc0 .Lh8_f
	v_lshlrev_b32_e32 v9, 6, v224
	v_lshlrev_b32_e32 v10, 2, v225
	v_bitop3_b32 v11, v9, 64, v10 bitop3:0x36
	s_branch .Lh8_ss

.Lh8_ss:
	ds_bpermute_b32 v2, v11, v142
	ds_bpermute_b32 v3, v11, v143
	ds_bpermute_b32 v4, v11, v130
	ds_bpermute_b32 v5, v11, v118
	ds_bpermute_b32 v6, v11, v50
	ds_bpermute_b32 v7, v11, v51
	ds_bpermute_b32 v8, v11, v28
	ds_bpermute_b32 v11, v11, v12
	s_waitcnt lgkmcnt(0)
	v_add_f32_e32 v2, v142, v2
	v_add_f32_e32 v3, v143, v3
	v_add_f32_e32 v4, v130, v4
	v_add_f32_e32 v5, v118, v5
	v_add_f32_e32 v6, v50, v6
	v_add_f32_e32 v7, v51, v7
	v_add_f32_e32 v8, v28, v8
	v_add_f32_e32 v12, v12, v11
	v_bitop3_b32 v17, v9, s90, v10 bitop3:0x36
	ds_bpermute_b32 v9, v17, v2
	ds_bpermute_b32 v10, v17, v3
	ds_bpermute_b32 v11, v17, v4
	ds_bpermute_b32 v13, v17, v5
	ds_bpermute_b32 v14, v17, v6
	ds_bpermute_b32 v15, v17, v7
	ds_bpermute_b32 v16, v17, v8
	ds_bpermute_b32 v17, v17, v12
	s_and_saveexec_b64 s[0:1], vcc
	s_cbranch_execz .LBB0_1321
	s_lshl_b32 s2, s88, 2
	s_ashr_i32 s3, s2, 31
	s_lshl_b64 s[2:3], s[2:3], 2
	s_add_u32 s2, s71, s2
	s_addc_u32 s3, s72, s3
	v_lshlrev_b32_e32 v0, 2, v0
	s_waitcnt lgkmcnt(4)
	v_add_f32_e32 v13, v5, v13
	v_add_f32_e32 v11, v4, v11
	v_add_f32_e32 v10, v3, v10
	v_add_f32_e32 v9, v2, v9
	v_lshl_add_u64 v[2:3], s[2:3], 0, v[0:1]
	v_lshlrev_b64 v[4:5], 6, v[198:199]
	v_lshl_add_u64 v[4:5], v[2:3], 0, v[4:5]
	global_store_dword v[4:5], v9, off
	v_lshlrev_b64 v[4:5], 6, v[218:219]
	v_lshl_add_u64 v[4:5], v[2:3], 0, v[4:5]
	global_store_dword v[4:5], v10, off
	v_lshlrev_b64 v[4:5], 6, v[138:139]
	v_lshl_add_u64 v[4:5], v[2:3], 0, v[4:5]
	global_store_dword v[4:5], v11, off
	v_lshlrev_b64 v[4:5], 6, v[140:141]
	v_lshl_add_u64 v[4:5], v[2:3], 0, v[4:5]
	global_store_dword v[4:5], v13, off
	s_cmp_lg_u32 s100, 0
	s_cbranch_scc0 .Lh8_g
	s_waitcnt lgkmcnt(0)
	s_branch .LBB0_1321
